# dilated attention: MFMA->VALU padding trimmed from 16 to the required 8 wait states (36 sites)
# baseline (speedup 1.0000x reference)
.LBB0_367:
	s_add_i32 s62, s63, 3
	s_add_i32 s38, s61, -16
	s_cmp_lt_i32 s62, 8
	s_cselect_b64 s[0:1], -1, 0
	s_and_b64 s[4:5], s[0:1], exec
	s_cselect_b32 s4, s38, 0x90
	s_add_i32 s4, s4, s57
	s_waitcnt vmcnt(11)
	v_or_b32_e32 v64, s4, v149
	v_med3_i32 v64, v64, 0, v244
	v_add_u32_e32 v65, s4, v194
	v_med3_i32 v65, v65, 0, v244
	v_mul_u32_u24_e32 v176, 0x2800, v64
	s_waitcnt vmcnt(10)
	v_lshl_add_u64 v[68:69], v[164:165], 0, v[176:177]
	v_mul_u32_u24_e32 v176, 0x2800, v65
	s_waitcnt vmcnt(8) lgkmcnt(1)
	v_lshl_add_u64 v[92:93], v[166:167], 0, v[176:177]
	global_load_dwordx4 v[64:67], v[68:69], off offset:1536
	s_nop 0
	global_load_dwordx4 v[68:71], v[68:69], off offset:1600
	s_nop 0
	global_load_dwordx4 v[88:91], v[92:93], off offset:3088
	s_waitcnt lgkmcnt(0)
	global_load_dwordx4 v[92:95], v[92:93], off offset:3072
	s_waitcnt vmcnt(6)
	ds_write_b128 v211, v[76:79]
	ds_write_b128 v211, v[72:75] offset:16
	ds_read_b64_tr_b16 v[72:73], v212
	ds_read_b64_tr_b16 v[74:75], v212 offset:32
	ds_read_b64_tr_b16 v[76:77], v212 offset:64
	ds_read_b64_tr_b16 v[78:79], v212 offset:96
	v_add_u32_e32 v104, s61, v102
	v_add_u32_e32 v105, 0xffffff50, v104
	s_cmp_lg_u32 s63, 6
	s_cselect_b64 s[4:5], -1, 0
	s_cmp_eq_u32 s63, 6
	v_add_u32_e32 v103, s61, v200
	v_cmp_lt_i32_e64 s[48:49], -1, v105
	v_cmp_lt_i32_e64 s[46:47], -2, v105
	v_cmp_lt_i32_e64 s[44:45], -3, v105
	v_cmp_lt_i32_e32 vcc, -4, v105
	s_cbranch_scc1 .LBB0_372
	v_subrev_u32_e32 v101, 48, v103
	v_cmp_gt_u32_e64 s[50:51], s16, v101
	s_waitcnt vmcnt(4)
	s_nop 1
	v_mfma_f32_16x16x32_bf16 v[106:109], v[52:55], v[12:15], 0
	v_mfma_f32_16x16x32_bf16 v[106:109], v[48:51], v[20:23], v[106:109]
	s_nop 7
	v_add_u32_e32 v100, 0xffffff50, v103
	s_and_b64 s[48:49], s[48:49], s[50:51]
	v_cndmask_b32_e64 v106, v245, v106, s[48:49]
	v_cmp_lt_u32_e64 s[48:49], s17, v100
	s_and_b64 s[46:47], s[46:47], s[48:49]
	v_subrev_u32_e32 v100, 46, v103
	v_cndmask_b32_e64 v107, v245, v107, s[46:47]
	v_cmp_gt_u32_e64 s[46:47], s16, v100
	s_and_b64 s[44:45], s[44:45], s[46:47]
	v_subrev_u32_e32 v100, 45, v103
	v_cndmask_b32_e64 v108, v245, v108, s[44:45]
	v_cmp_gt_u32_e64 s[44:45], s16, v100
	s_and_b64 vcc, vcc, s[44:45]
	v_cndmask_b32_e32 v109, v245, v109, vcc
	v_max_f32_e32 v100, v109, v109
	v_max_f32_e32 v101, v108, v108
	v_max_f32_e32 v100, v101, v100
	v_max3_f32 v100, v106, v107, v100
	ds_swizzle_b32 v101, v100 offset:swizzle(SWAP,16)
	s_waitcnt lgkmcnt(0)
	v_max_f32_e32 v101, v101, v101
	v_max_f32_e32 v100, v100, v101
	v_mov_b32_e32 v101, v100
	s_nop 1
	v_permlane32_swap_b32_e32 v100, v101
	v_max_f32_e32 v101, v101, v101
	v_max_f32_e32 v100, v100, v100
	v_max_f32_e32 v100, v100, v101
	v_mul_f32_e32 v100, 0x3e38aa3b, v100
	v_add_f32_e32 v101, 0x41000000, v98
	v_cmp_gt_f32_e32 vcc, v100, v101
	s_cbranch_vccz .LBB0_370
	s_nop 0
	v_cndmask_b32_e32 v100, v98, v100, vcc
	v_sub_f32_e32 v98, v98, v100
	v_exp_f32_e32 v98, v98
	v_mov_b32_e32 v101, v99
	v_mul_f32_e32 v96, v96, v98
	v_pk_mul_f32 v[46:47], v[46:47], v[98:99] op_sel_hi:[1,0]
	v_pk_mul_f32 v[44:45], v[44:45], v[98:99] op_sel_hi:[1,0]
	v_pk_mul_f32 v[38:39], v[38:39], v[98:99] op_sel_hi:[1,0]
	v_pk_mul_f32 v[36:37], v[36:37], v[98:99] op_sel_hi:[1,0]
	v_pk_mul_f32 v[42:43], v[42:43], v[98:99] op_sel_hi:[1,0]
	v_pk_mul_f32 v[40:41], v[40:41], v[98:99] op_sel_hi:[1,0]
	v_pk_mul_f32 v[34:35], v[34:35], v[98:99] op_sel_hi:[1,0]
	v_pk_mul_f32 v[32:33], v[32:33], v[98:99] op_sel_hi:[1,0]
	v_mov_b64_e32 v[98:99], v[100:101]
	s_branch .LBB0_371

.LBB0_371:
	v_fma_f32 v101, v106, s18, -v100
	v_exp_f32_e32 v106, v101
	v_fma_f32 v101, v107, s18, -v100
	v_exp_f32_e32 v110, v101
	v_fma_f32 v101, v108, s18, -v100
	v_fma_f32 v100, v109, s18, -v100
	v_exp_f32_e32 v107, v101
	v_exp_f32_e32 v111, v100
	s_nop 0
	v_pk_add_f32 v[100:101], v[106:107], v[110:111]
	s_nop 0
	v_pk_add_f32 v[100:101], v[100:101], v[100:101] op_sel:[0,1] op_sel_hi:[1,0]
	s_nop 0
	v_pk_add_f32 v[100:101], v[96:97], v[100:101]
	v_cvt_pk_bf16_f32 v96, v106, v110
	s_nop 0
	v_mov_b32_e32 v101, v97
	v_cvt_pk_bf16_f32 v97, v107, v111
	s_nop 0
	s_nop 1
	v_mfma_f32_16x16x16_bf16 v[44:47], v[72:73], v[96:97], v[44:47]
	v_mfma_f32_16x16x16_bf16 v[36:39], v[74:75], v[96:97], v[36:39]
	v_mfma_f32_16x16x16_bf16 v[40:43], v[76:77], v[96:97], v[40:43]
	v_mfma_f32_16x16x16_bf16 v[32:35], v[78:79], v[96:97], v[32:35]
	s_nop 7
	v_mov_b64_e32 v[96:97], v[100:101]
.LBB0_372:
	s_cmp_lt_i32 s62, 1
	s_cbranch_scc1 .LBB0_377
	s_waitcnt vmcnt(4)
	s_nop 1
	v_mfma_f32_16x16x32_bf16 v[106:109], v[52:55], v[24:27], 0
	v_mfma_f32_16x16x32_bf16 v[106:109], v[48:51], v[28:31], v[106:109]
	s_nop 7
	v_subrev_u32_e32 v48, 64, v103
	v_cmp_gt_u32_e32 vcc, s16, v48
	v_cmp_lt_i32_e64 s[44:45], -1, v105
	v_add_u32_e32 v49, 0xffffff40, v103
	s_and_b64 vcc, s[44:45], vcc
	v_cndmask_b32_e32 v48, v245, v106, vcc
	v_cmp_lt_u32_e32 vcc, s17, v49
	v_cmp_lt_i32_e64 s[44:45], -2, v105
	s_and_b64 vcc, s[44:45], vcc
	v_subrev_u32_e32 v50, 62, v103
	v_cndmask_b32_e32 v49, v245, v107, vcc
	v_cmp_gt_u32_e32 vcc, s16, v50
	v_cmp_lt_i32_e64 s[44:45], -3, v105
	s_and_b64 vcc, s[44:45], vcc
	v_subrev_u32_e32 v51, 61, v103
	v_cndmask_b32_e32 v50, v245, v108, vcc
	v_cmp_gt_u32_e32 vcc, s16, v51
	v_cmp_lt_i32_e64 s[44:45], -4, v105
	s_and_b64 vcc, s[44:45], vcc
	v_cndmask_b32_e32 v51, v245, v109, vcc
	v_max_f32_e32 v52, v51, v51
	v_max_f32_e32 v53, v50, v50
	v_max_f32_e32 v52, v53, v52
	v_max3_f32 v52, v48, v49, v52
	ds_swizzle_b32 v53, v52 offset:swizzle(SWAP,16)
	s_waitcnt lgkmcnt(0)
	v_max_f32_e32 v53, v53, v53
	v_max_f32_e32 v52, v52, v53
	v_mov_b32_e32 v53, v52
	s_nop 1
	v_permlane32_swap_b32_e32 v52, v53
	v_max_f32_e32 v53, v53, v53
	v_max_f32_e32 v52, v52, v52
	v_max_f32_e32 v52, v52, v53
	v_mul_f32_e32 v52, 0x3e38aa3b, v52
	v_add_f32_e32 v53, 0x41000000, v99
	v_cmp_gt_f32_e32 vcc, v52, v53
	s_cbranch_vccz .LBB0_375
	s_nop 0
	v_cndmask_b32_e32 v52, v99, v52, vcc
	v_sub_f32_e32 v53, v99, v52
	v_exp_f32_e32 v54, v53
	v_mov_b32_e32 v99, v52
	v_mul_f32_e32 v97, v97, v54
	v_pk_mul_f32 v[18:19], v[18:19], v[54:55] op_sel_hi:[1,0]
	v_pk_mul_f32 v[16:17], v[16:17], v[54:55] op_sel_hi:[1,0]
	v_pk_mul_f32 v[10:11], v[10:11], v[54:55] op_sel_hi:[1,0]
	v_pk_mul_f32 v[8:9], v[8:9], v[54:55] op_sel_hi:[1,0]
	v_pk_mul_f32 v[6:7], v[6:7], v[54:55] op_sel_hi:[1,0]
	v_pk_mul_f32 v[4:5], v[4:5], v[54:55] op_sel_hi:[1,0]
	v_pk_mul_f32 v[2:3], v[2:3], v[54:55] op_sel_hi:[1,0]
	v_pk_mul_f32 v[0:1], v[0:1], v[54:55] op_sel_hi:[1,0]
	s_branch .LBB0_376

.LBB0_377:
	s_cmp_gt_i32 s62, 6
	s_cselect_b64 s[38:39], -1, 0
	s_cmp_lt_i32 s62, 7
	s_cselect_b32 s44, s61, 0x90
	s_add_i32 s44, s44, s57
	s_waitcnt vmcnt(5)
	v_or_b32_e32 v48, s44, v149
	v_med3_i32 v48, v48, 0, v244
	v_add_u32_e32 v49, s44, v194
	v_med3_i32 v50, v49, 0, v244
	v_mul_u32_u24_e32 v176, 0x2800, v48
	v_lshl_add_u64 v[48:49], v[164:165], 0, v[176:177]
	v_mul_u32_u24_e32 v176, 0x2800, v50
	s_waitcnt lgkmcnt(1)
	v_lshl_add_u64 v[76:77], v[166:167], 0, v[176:177]
	global_load_dwordx4 v[52:55], v[48:49], off offset:1536
	s_nop 0
	global_load_dwordx4 v[48:51], v[48:49], off offset:1600
	s_nop 0
	global_load_dwordx4 v[72:75], v[76:77], off offset:3088
	s_waitcnt lgkmcnt(0)
	global_load_dwordx4 v[76:79], v[76:77], off offset:3072
	v_cndmask_b32_e64 v100, 0, 1, s[0:1]
	s_andn2_b64 vcc, exec, s[4:5]
	v_cmp_ne_u32_e64 s[44:45], 1, v100
	s_cbranch_vccnz .LBB0_388
	s_waitcnt vmcnt(8)
	ds_write_b128 v211, v[84:87]
	ds_write_b128 v211, v[80:83] offset:16
	ds_read_b64_tr_b16 v[80:81], v212
	ds_read_b64_tr_b16 v[82:83], v212 offset:32
	ds_read_b64_tr_b16 v[84:85], v212 offset:64
	ds_read_b64_tr_b16 v[86:87], v212 offset:96
	v_add_u32_e32 v105, 0xffffff60, v104
	s_and_b64 vcc, exec, s[44:45]
	v_cmp_lt_i32_e64 s[52:53], -1, v105
	v_cmp_lt_i32_e64 s[50:51], -2, v105
	v_cmp_lt_i32_e64 s[48:49], -3, v105
	v_cmp_lt_i32_e64 s[46:47], -4, v105
	s_cbranch_vccnz .LBB0_383
	v_subrev_u32_e32 v101, 32, v103
	v_cmp_gt_u32_e32 vcc, s16, v101
	s_nop 1
	v_mfma_f32_16x16x32_bf16 v[106:109], v[56:59], v[12:15], 0
	v_mfma_f32_16x16x32_bf16 v[106:109], v[60:63], v[20:23], v[106:109]
	s_nop 7
	v_add_u32_e32 v100, 0xffffff60, v103
	s_and_b64 vcc, s[52:53], vcc
	v_cndmask_b32_e32 v106, v245, v106, vcc
	v_cmp_lt_u32_e32 vcc, s17, v100
	s_and_b64 vcc, s[50:51], vcc
	v_subrev_u32_e32 v100, 30, v103
	v_cndmask_b32_e32 v107, v245, v107, vcc
	v_cmp_gt_u32_e32 vcc, s16, v100
	s_and_b64 vcc, s[48:49], vcc
	v_subrev_u32_e32 v100, 29, v103
	v_cndmask_b32_e32 v108, v245, v108, vcc
	v_cmp_gt_u32_e32 vcc, s16, v100
	s_and_b64 vcc, s[46:47], vcc
	v_max_f32_e32 v101, v108, v108
	v_cndmask_b32_e32 v109, v245, v109, vcc
	v_max_f32_e32 v100, v109, v109
	v_max_f32_e32 v100, v101, v100
	v_max3_f32 v100, v106, v107, v100
	ds_swizzle_b32 v101, v100 offset:swizzle(SWAP,16)
	s_waitcnt lgkmcnt(0)
	v_max_f32_e32 v101, v101, v101
	v_max_f32_e32 v100, v100, v101
	v_mov_b32_e32 v101, v100
	s_nop 1
	v_permlane32_swap_b32_e32 v100, v101
	v_max_f32_e32 v101, v101, v101
	v_max_f32_e32 v100, v100, v100
	v_max_f32_e32 v100, v100, v101
	v_mul_f32_e32 v100, 0x3e38aa3b, v100
	v_add_f32_e32 v101, 0x41000000, v98
	v_cmp_gt_f32_e32 vcc, v100, v101
	s_cbranch_vccz .LBB0_381
	s_nop 0
	v_cndmask_b32_e32 v100, v98, v100, vcc
	v_sub_f32_e32 v98, v98, v100
	v_exp_f32_e32 v98, v98
	v_mov_b32_e32 v101, v99
	v_mul_f32_e32 v96, v96, v98
	v_pk_mul_f32 v[46:47], v[46:47], v[98:99] op_sel_hi:[1,0]
	v_pk_mul_f32 v[44:45], v[44:45], v[98:99] op_sel_hi:[1,0]
	v_pk_mul_f32 v[38:39], v[38:39], v[98:99] op_sel_hi:[1,0]
	v_pk_mul_f32 v[36:37], v[36:37], v[98:99] op_sel_hi:[1,0]
	v_pk_mul_f32 v[42:43], v[42:43], v[98:99] op_sel_hi:[1,0]
	v_pk_mul_f32 v[40:41], v[40:41], v[98:99] op_sel_hi:[1,0]
	v_pk_mul_f32 v[34:35], v[34:35], v[98:99] op_sel_hi:[1,0]
	v_pk_mul_f32 v[32:33], v[32:33], v[98:99] op_sel_hi:[1,0]
	v_mov_b64_e32 v[98:99], v[100:101]
	s_branch .LBB0_382

.LBB0_382:
	v_fma_f32 v101, v106, s18, -v100
	v_exp_f32_e32 v106, v101
	v_fma_f32 v101, v107, s18, -v100
	v_exp_f32_e32 v110, v101
	v_fma_f32 v101, v108, s18, -v100
	v_fma_f32 v100, v109, s18, -v100
	v_exp_f32_e32 v107, v101
	v_exp_f32_e32 v111, v100
	s_nop 0
	v_pk_add_f32 v[100:101], v[106:107], v[110:111]
	s_nop 0
	v_pk_add_f32 v[100:101], v[100:101], v[100:101] op_sel:[0,1] op_sel_hi:[1,0]
	s_nop 0
	v_pk_add_f32 v[100:101], v[96:97], v[100:101]
	v_cvt_pk_bf16_f32 v96, v106, v110
	s_nop 0
	v_mov_b32_e32 v101, v97
	v_cvt_pk_bf16_f32 v97, v107, v111
	s_nop 0
	s_nop 1
	v_mfma_f32_16x16x16_bf16 v[44:47], v[80:81], v[96:97], v[44:47]
	v_mfma_f32_16x16x16_bf16 v[36:39], v[82:83], v[96:97], v[36:39]
	v_mfma_f32_16x16x16_bf16 v[40:43], v[84:85], v[96:97], v[40:43]
	v_mfma_f32_16x16x16_bf16 v[32:35], v[86:87], v[96:97], v[32:35]
	s_nop 7
	v_mov_b64_e32 v[96:97], v[100:101]
.LBB0_383:
	s_cmp_lt_i32 s62, 0
	s_cbranch_scc1 .LBB0_388
	s_nop 1
	v_mfma_f32_16x16x32_bf16 v[106:109], v[56:59], v[24:27], 0
	v_mfma_f32_16x16x32_bf16 v[106:109], v[60:63], v[28:31], v[106:109]
	s_nop 7
	v_subrev_u32_e32 v56, 48, v103
	v_cmp_gt_u32_e32 vcc, s16, v56
	v_cmp_lt_i32_e64 s[46:47], -1, v105
	v_add_u32_e32 v57, 0xffffff50, v103
	s_and_b64 vcc, s[46:47], vcc
	v_cndmask_b32_e32 v56, v245, v106, vcc
	v_cmp_lt_u32_e32 vcc, s17, v57
	v_cmp_lt_i32_e64 s[46:47], -2, v105
	s_and_b64 vcc, s[46:47], vcc
	v_subrev_u32_e32 v58, 46, v103
	v_cndmask_b32_e32 v57, v245, v107, vcc
	v_cmp_gt_u32_e32 vcc, s16, v58
	v_cmp_lt_i32_e64 s[46:47], -3, v105
	s_and_b64 vcc, s[46:47], vcc
	v_subrev_u32_e32 v59, 45, v103
	v_cndmask_b32_e32 v58, v245, v108, vcc
	v_cmp_gt_u32_e32 vcc, s16, v59
	v_cmp_lt_i32_e64 s[46:47], -4, v105
	s_and_b64 vcc, s[46:47], vcc
	v_cndmask_b32_e32 v59, v245, v109, vcc
	v_max_f32_e32 v60, v59, v59
	v_max_f32_e32 v61, v58, v58
	v_max_f32_e32 v60, v61, v60
	v_max3_f32 v60, v56, v57, v60
	ds_swizzle_b32 v61, v60 offset:swizzle(SWAP,16)
	s_waitcnt lgkmcnt(0)
	v_max_f32_e32 v61, v61, v61
	v_max_f32_e32 v60, v60, v61
	v_mov_b32_e32 v61, v60
	s_nop 1
	v_permlane32_swap_b32_e32 v60, v61
	v_max_f32_e32 v61, v61, v61
	v_max_f32_e32 v60, v60, v60
	v_max_f32_e32 v60, v60, v61
	v_mul_f32_e32 v60, 0x3e38aa3b, v60
	v_add_f32_e32 v61, 0x41000000, v99
	v_cmp_gt_f32_e32 vcc, v60, v61
	s_cbranch_vccz .LBB0_386
	s_nop 0
	v_cndmask_b32_e32 v60, v99, v60, vcc
	v_sub_f32_e32 v61, v99, v60
	v_exp_f32_e32 v62, v61
	v_mov_b32_e32 v99, v60
	v_mul_f32_e32 v97, v97, v62
	v_pk_mul_f32 v[18:19], v[18:19], v[62:63] op_sel_hi:[1,0]
	v_pk_mul_f32 v[16:17], v[16:17], v[62:63] op_sel_hi:[1,0]
	v_pk_mul_f32 v[10:11], v[10:11], v[62:63] op_sel_hi:[1,0]
	v_pk_mul_f32 v[8:9], v[8:9], v[62:63] op_sel_hi:[1,0]
	v_pk_mul_f32 v[6:7], v[6:7], v[62:63] op_sel_hi:[1,0]
	v_pk_mul_f32 v[4:5], v[4:5], v[62:63] op_sel_hi:[1,0]
	v_pk_mul_f32 v[2:3], v[2:3], v[62:63] op_sel_hi:[1,0]
	v_pk_mul_f32 v[0:1], v[0:1], v[62:63] op_sel_hi:[1,0]
	s_branch .LBB0_387

.LBB0_388:
	s_min_i32 s0, s62, 5
	s_lshl_b32 s0, s0, 4
	s_add_i32 s0, s60, s0
	v_or_b32_e32 v56, s0, v149
	v_med3_i32 v56, v56, 0, v244
	v_add_u32_e32 v57, s0, v194
	v_med3_i32 v57, v57, 0, v244
	v_mul_u32_u24_e32 v176, 0x2800, v56
	v_lshl_add_u64 v[60:61], v[164:165], 0, v[176:177]
	v_mul_u32_u24_e32 v176, 0x2800, v57
	s_waitcnt vmcnt(8) lgkmcnt(1)
	v_lshl_add_u64 v[84:85], v[166:167], 0, v[176:177]
	global_load_dwordx4 v[56:59], v[60:61], off offset:1536
	s_nop 0
	global_load_dwordx4 v[60:63], v[60:61], off offset:1600
	s_nop 0
	global_load_dwordx4 v[80:83], v[84:85], off offset:3088
	s_waitcnt lgkmcnt(0)
	global_load_dwordx4 v[84:87], v[84:85], off offset:3072
	s_and_b64 vcc, exec, s[44:45]
	s_cbranch_vccnz .LBB0_399
	s_waitcnt vmcnt(8)
	ds_write_b128 v211, v[92:95]
	ds_write_b128 v211, v[88:91] offset:16
	ds_read_b64_tr_b16 v[88:89], v212
	ds_read_b64_tr_b16 v[90:91], v212 offset:32
	ds_read_b64_tr_b16 v[92:93], v212 offset:64
	ds_read_b64_tr_b16 v[94:95], v212 offset:96
	v_add_u32_e32 v104, 0xffffff70, v104
	s_cmp_eq_u32 s63, 4
	v_cmp_lt_i32_e64 s[48:49], -1, v104
	v_cmp_lt_i32_e64 s[46:47], -2, v104
	v_cmp_lt_i32_e64 s[44:45], -3, v104
	v_cmp_lt_i32_e32 vcc, -4, v104
	s_cbranch_scc1 .LBB0_394
	v_add_u32_e32 v101, -16, v103
	v_cmp_gt_u32_e64 s[50:51], s16, v101
	v_add_u32_e32 v100, 0xffffff70, v103
	s_and_b64 s[48:49], s[48:49], s[50:51]
	s_nop 1
	v_mfma_f32_16x16x32_bf16 v[106:109], v[64:67], v[12:15], 0
	v_mfma_f32_16x16x32_bf16 v[106:109], v[68:71], v[20:23], v[106:109]
	s_nop 7
	s_nop 0
	v_cndmask_b32_e64 v105, v245, v106, s[48:49]
	v_cmp_lt_u32_e64 s[48:49], s17, v100
	s_and_b64 s[46:47], s[46:47], s[48:49]
	v_add_u32_e32 v100, -14, v103
	v_cndmask_b32_e64 v106, v245, v107, s[46:47]
	v_cmp_gt_u32_e64 s[46:47], s16, v100
	s_and_b64 s[44:45], s[44:45], s[46:47]
	v_add_u32_e32 v100, -13, v103
	v_cndmask_b32_e64 v107, v245, v108, s[44:45]
	v_cmp_gt_u32_e64 s[44:45], s16, v100
	s_and_b64 vcc, vcc, s[44:45]
	v_cndmask_b32_e32 v108, v245, v109, vcc
	v_max_f32_e32 v100, v108, v108
	v_max_f32_e32 v101, v107, v107
	v_max_f32_e32 v100, v101, v100
	v_max3_f32 v100, v105, v106, v100
	ds_swizzle_b32 v101, v100 offset:swizzle(SWAP,16)
	s_waitcnt lgkmcnt(0)
	v_max_f32_e32 v101, v101, v101
	v_max_f32_e32 v100, v100, v101
	v_mov_b32_e32 v101, v100
	s_nop 1
	v_permlane32_swap_b32_e32 v100, v101
	v_max_f32_e32 v101, v101, v101
	v_max_f32_e32 v100, v100, v100
	v_max_f32_e32 v100, v100, v101
	v_mul_f32_e32 v100, 0x3e38aa3b, v100
	v_add_f32_e32 v101, 0x41000000, v98
	v_cmp_gt_f32_e32 vcc, v100, v101
	s_cbranch_vccz .LBB0_392
	s_nop 0
	v_cndmask_b32_e32 v100, v98, v100, vcc
	v_sub_f32_e32 v98, v98, v100
	v_exp_f32_e32 v98, v98
	v_mov_b32_e32 v101, v99
	v_mul_f32_e32 v96, v96, v98
	v_pk_mul_f32 v[46:47], v[46:47], v[98:99] op_sel_hi:[1,0]
	v_pk_mul_f32 v[44:45], v[44:45], v[98:99] op_sel_hi:[1,0]
	v_pk_mul_f32 v[38:39], v[38:39], v[98:99] op_sel_hi:[1,0]
	v_pk_mul_f32 v[36:37], v[36:37], v[98:99] op_sel_hi:[1,0]
	v_pk_mul_f32 v[42:43], v[42:43], v[98:99] op_sel_hi:[1,0]
	v_pk_mul_f32 v[40:41], v[40:41], v[98:99] op_sel_hi:[1,0]
	v_pk_mul_f32 v[34:35], v[34:35], v[98:99] op_sel_hi:[1,0]
	v_pk_mul_f32 v[32:33], v[32:33], v[98:99] op_sel_hi:[1,0]
	v_mov_b64_e32 v[98:99], v[100:101]
	s_branch .LBB0_393

.LBB0_393:
	v_fma_f32 v101, v105, s18, -v100
	v_exp_f32_e32 v110, v101
	v_fma_f32 v101, v106, s18, -v100
	v_exp_f32_e32 v106, v101
	v_fma_f32 v101, v107, s18, -v100
	v_fma_f32 v100, v108, s18, -v100
	v_exp_f32_e32 v111, v101
	v_exp_f32_e32 v107, v100
	s_nop 0
	v_pk_add_f32 v[100:101], v[110:111], v[106:107]
	s_nop 0
	v_pk_add_f32 v[100:101], v[100:101], v[100:101] op_sel:[0,1] op_sel_hi:[1,0]
	s_nop 0
	v_pk_add_f32 v[100:101], v[96:97], v[100:101]
	v_cvt_pk_bf16_f32 v96, v110, v106
	s_nop 0
	v_mov_b32_e32 v101, v97
	v_cvt_pk_bf16_f32 v97, v111, v107
	s_nop 0
	s_nop 1
	v_mfma_f32_16x16x16_bf16 v[44:47], v[88:89], v[96:97], v[44:47]
	v_mfma_f32_16x16x16_bf16 v[36:39], v[90:91], v[96:97], v[36:39]
	v_mfma_f32_16x16x16_bf16 v[40:43], v[92:93], v[96:97], v[40:43]
	v_mfma_f32_16x16x16_bf16 v[32:35], v[94:95], v[96:97], v[32:35]
	s_nop 7
	v_mov_b64_e32 v[96:97], v[100:101]
.LBB0_394:
	s_cmp_lt_i32 s62, -1
	s_cbranch_scc1 .LBB0_399
	s_nop 1
	v_mfma_f32_16x16x32_bf16 v[106:109], v[64:67], v[24:27], 0
	v_mfma_f32_16x16x32_bf16 v[106:109], v[68:71], v[28:31], v[106:109]
	s_nop 7
	v_subrev_u32_e32 v64, 32, v103
	v_cmp_gt_u32_e32 vcc, s16, v64
	v_cmp_lt_i32_e64 s[44:45], -1, v104
	v_add_u32_e32 v65, 0xffffff60, v103
	s_and_b64 vcc, s[44:45], vcc
	v_cndmask_b32_e32 v64, v245, v106, vcc
	v_cmp_lt_u32_e32 vcc, s17, v65
	v_cmp_lt_i32_e64 s[44:45], -2, v104
	s_and_b64 vcc, s[44:45], vcc
	v_subrev_u32_e32 v66, 30, v103
	v_cndmask_b32_e32 v65, v245, v107, vcc
	v_cmp_gt_u32_e32 vcc, s16, v66
	v_cmp_lt_i32_e64 s[44:45], -3, v104
	s_and_b64 vcc, s[44:45], vcc
	v_subrev_u32_e32 v67, 29, v103
	v_cndmask_b32_e32 v66, v245, v108, vcc
	v_cmp_gt_u32_e32 vcc, s16, v67
	v_cmp_lt_i32_e64 s[44:45], -4, v104
	s_and_b64 vcc, s[44:45], vcc
	v_cndmask_b32_e32 v67, v245, v109, vcc
	v_max_f32_e32 v68, v67, v67
	v_max_f32_e32 v69, v66, v66
	v_max_f32_e32 v68, v69, v68
	v_max3_f32 v68, v64, v65, v68
	ds_swizzle_b32 v69, v68 offset:swizzle(SWAP,16)
	s_waitcnt lgkmcnt(0)
	v_max_f32_e32 v69, v69, v69
	v_max_f32_e32 v68, v68, v69
	v_mov_b32_e32 v69, v68
	s_nop 1
	v_permlane32_swap_b32_e32 v68, v69
	v_max_f32_e32 v69, v69, v69
	v_max_f32_e32 v68, v68, v68
	v_max_f32_e32 v68, v68, v69
	v_mul_f32_e32 v68, 0x3e38aa3b, v68
	v_add_f32_e32 v69, 0x41000000, v99
	v_cmp_gt_f32_e32 vcc, v68, v69
	s_cbranch_vccz .LBB0_397
	s_nop 0
	v_cndmask_b32_e32 v68, v99, v68, vcc
	v_sub_f32_e32 v69, v99, v68
	v_exp_f32_e32 v70, v69
	v_mov_b32_e32 v99, v68
	v_mul_f32_e32 v97, v97, v70
	v_pk_mul_f32 v[18:19], v[18:19], v[70:71] op_sel_hi:[1,0]
	v_pk_mul_f32 v[16:17], v[16:17], v[70:71] op_sel_hi:[1,0]
	v_pk_mul_f32 v[10:11], v[10:11], v[70:71] op_sel_hi:[1,0]
	v_pk_mul_f32 v[8:9], v[8:9], v[70:71] op_sel_hi:[1,0]
	v_pk_mul_f32 v[6:7], v[6:7], v[70:71] op_sel_hi:[1,0]
	v_pk_mul_f32 v[4:5], v[4:5], v[70:71] op_sel_hi:[1,0]
	v_pk_mul_f32 v[2:3], v[2:3], v[70:71] op_sel_hi:[1,0]
	v_pk_mul_f32 v[0:1], v[0:1], v[70:71] op_sel_hi:[1,0]
	s_branch .LBB0_398

.LBB0_398:
	v_fma_f32 v65, v65, s18, -v68
	v_fma_f32 v64, v64, s18, -v68
	v_exp_f32_e32 v70, v65
	v_fma_f32 v65, v66, s18, -v68
	v_fma_f32 v66, v67, s18, -v68
	v_exp_f32_e32 v64, v64
	v_exp_f32_e32 v65, v65
	v_exp_f32_e32 v71, v66
	s_nop 0
	v_pk_add_f32 v[66:67], v[64:65], v[70:71]
	s_nop 0
	v_add_f32_e32 v66, v66, v67
	v_pk_add_f32 v[66:67], v[96:97], v[66:67] op_sel_hi:[1,0]
	v_cvt_pk_bf16_f32 v64, v64, v70
	v_cvt_pk_bf16_f32 v65, v65, v71
	s_nop 0
	v_mov_b32_e32 v97, v67
	s_nop 1
	v_mfma_f32_16x16x16_bf16 v[16:19], v[88:89], v[64:65], v[16:19]
	v_mfma_f32_16x16x16_bf16 v[8:11], v[90:91], v[64:65], v[8:11]
	v_mfma_f32_16x16x16_bf16 v[4:7], v[92:93], v[64:65], v[4:7]
	v_mfma_f32_16x16x16_bf16 v[0:3], v[94:95], v[64:65], v[0:3]
	s_nop 7
.LBB0_399:
	s_add_i32 s61, s61, 48
	s_and_b64 vcc, exec, s[38:39]
	s_cbranch_vccnz .LBB0_401
	s_mov_b32 s63, s62
	s_branch .LBB0_367

.LBB0_407:
	s_cmp_gt_u32 s62, 7
	s_cselect_b64 s[0:1], -1, 0
	s_add_i32 s38, s64, -16
	s_cmp_lt_u32 s62, 8
	s_cselect_b64 s[52:53], -1, 0
	s_and_b64 s[4:5], s[52:53], exec
	s_cselect_b32 s4, s38, 0x90
	s_add_i32 s4, s4, s61
	s_waitcnt vmcnt(11)
	v_or_b32_e32 v48, s4, v149
	v_lshl_add_u32 v48, v48, 2, s8
	v_add_u32_e32 v49, s4, v194
	v_med3_i32 v48, v48, 0, v244
	v_lshl_add_u32 v49, v49, 2, s8
	v_med3_i32 v49, v49, 0, v244
	v_mul_u32_u24_e32 v176, 0x2800, v48
	s_waitcnt vmcnt(10)
	v_lshl_add_u64 v[52:53], v[164:165], 0, v[176:177]
	v_mul_u32_u24_e32 v176, 0x2800, v49
	s_waitcnt vmcnt(8)
	v_lshl_add_u64 v[96:97], v[166:167], 0, v[176:177]
	global_load_dwordx4 v[48:51], v[52:53], off offset:2048
	s_nop 0
	global_load_dwordx4 v[52:55], v[52:53], off offset:2112
	s_nop 0
	global_load_dwordx4 v[92:95], v[96:97], off offset:3600
	s_nop 0
	global_load_dwordx4 v[96:99], v[96:97], off offset:3584
	s_waitcnt vmcnt(6)
	ds_write_b128 v211, v[60:63]
	ds_write_b128 v211, v[56:59] offset:16
	ds_read_b64_tr_b16 v[56:57], v212
	ds_read_b64_tr_b16 v[58:59], v212 offset:32
	ds_read_b64_tr_b16 v[60:61], v212 offset:64
	ds_read_b64_tr_b16 v[62:63], v212 offset:96
	v_add_u32_e32 v172, s64, v155
	v_add_u32_e32 v112, 0xffffff50, v172
	s_cmpk_lg_i32 s64, 0xc0
	s_cselect_b64 s[4:5], -1, 0
	s_cmpk_eq_i32 s64, 0xc0
	v_cmp_lt_i32_e64 s[48:49], -1, v112
	v_cmp_lt_i32_e64 s[46:47], -2, v112
	v_cmp_lt_i32_e64 s[44:45], -3, v112
	v_cmp_lt_i32_e32 vcc, -4, v112
	v_add_u32_e32 v213, s64, v200
	s_cbranch_scc1 .LBB0_412
	v_add_u32_e32 v88, s64, v200
	v_subrev_u32_e32 v90, 48, v88
	v_cmp_gt_u32_e64 s[50:51], s16, v90
	v_add_u32_e32 v89, 0xffffff50, v88
	s_and_b64 s[48:49], s[48:49], s[50:51]
	s_waitcnt vmcnt(4)
	s_nop 1
	v_mfma_f32_16x16x32_bf16 v[100:103], v[44:47], v[16:19], 0
	v_mfma_f32_16x16x32_bf16 v[100:103], v[40:43], v[20:23], v[100:103]
	s_nop 7
	s_nop 0
	v_cndmask_b32_e64 v90, v245, v100, s[48:49]
	v_cmp_lt_u32_e64 s[48:49], s17, v89
	s_and_b64 s[46:47], s[46:47], s[48:49]
	v_subrev_u32_e32 v89, 46, v88
	v_cndmask_b32_e64 v91, v245, v101, s[46:47]
	v_cmp_gt_u32_e64 s[46:47], s16, v89
	s_and_b64 s[44:45], s[44:45], s[46:47]
	v_subrev_u32_e32 v88, 45, v88
	v_cndmask_b32_e64 v100, v245, v102, s[44:45]
	v_cmp_gt_u32_e64 s[44:45], s16, v88
	s_and_b64 vcc, vcc, s[44:45]
	v_cndmask_b32_e32 v101, v245, v103, vcc
	v_max_f32_e32 v88, v101, v101
	v_max_f32_e32 v89, v100, v100
	v_max_f32_e32 v88, v89, v88
	v_max3_f32 v88, v90, v91, v88
	ds_swizzle_b32 v89, v88 offset:swizzle(SWAP,16)
	s_waitcnt lgkmcnt(0)
	v_max_f32_e32 v89, v89, v89
	v_max_f32_e32 v88, v88, v89
	v_mov_b32_e32 v89, v88
	s_nop 1
	v_permlane32_swap_b32_e32 v88, v89
	v_max_f32_e32 v89, v89, v89
	v_max_f32_e32 v88, v88, v88
	v_max_f32_e32 v88, v88, v89
	v_mul_f32_e32 v88, 0x3e38aa3b, v88
	v_add_f32_e32 v89, 0x41000000, v168
	v_cmp_gt_f32_e32 vcc, v88, v89
	s_cbranch_vccz .LBB0_410
	s_nop 0
	v_cndmask_b32_e32 v88, v168, v88, vcc
	v_sub_f32_e32 v89, v168, v88
	v_exp_f32_e32 v102, v89
	v_mov_b32_e32 v89, v169
	v_mov_b64_e32 v[168:169], v[88:89]
	v_mul_f32_e32 v170, v170, v102
	v_pk_mul_f32 v[86:87], v[86:87], v[102:103] op_sel_hi:[1,0]
	v_pk_mul_f32 v[84:85], v[84:85], v[102:103] op_sel_hi:[1,0]
	v_pk_mul_f32 v[82:83], v[82:83], v[102:103] op_sel_hi:[1,0]
	v_pk_mul_f32 v[80:81], v[80:81], v[102:103] op_sel_hi:[1,0]
	v_pk_mul_f32 v[78:79], v[78:79], v[102:103] op_sel_hi:[1,0]
	v_pk_mul_f32 v[76:77], v[76:77], v[102:103] op_sel_hi:[1,0]
	v_pk_mul_f32 v[74:75], v[74:75], v[102:103] op_sel_hi:[1,0]
	v_pk_mul_f32 v[72:73], v[72:73], v[102:103] op_sel_hi:[1,0]
	s_branch .LBB0_411

.LBB0_411:
	v_fma_f32 v89, v90, s18, -v88
	v_exp_f32_e32 v90, v89
	v_fma_f32 v89, v91, s18, -v88
	v_exp_f32_e32 v102, v89
	v_fma_f32 v89, v100, s18, -v88
	v_fma_f32 v88, v101, s18, -v88
	v_exp_f32_e32 v91, v89
	v_exp_f32_e32 v103, v88
	s_nop 0
	v_pk_add_f32 v[88:89], v[90:91], v[102:103]
	s_nop 0
	v_pk_add_f32 v[88:89], v[88:89], v[88:89] op_sel:[0,1] op_sel_hi:[1,0]
	v_cvt_pk_bf16_f32 v90, v90, v102
	v_cvt_pk_bf16_f32 v91, v91, v103
	s_nop 0
	v_pk_add_f32 v[88:89], v[170:171], v[88:89]
	s_nop 1
	v_mfma_f32_16x16x16_bf16 v[84:87], v[56:57], v[90:91], v[84:87]
	v_mfma_f32_16x16x16_bf16 v[80:83], v[58:59], v[90:91], v[80:83]
	v_mfma_f32_16x16x16_bf16 v[76:79], v[60:61], v[90:91], v[76:79]
	v_mfma_f32_16x16x16_bf16 v[72:75], v[62:63], v[90:91], v[72:75]
	s_nop 7
	s_nop 0
	v_mov_b32_e32 v89, v171
	v_mov_b64_e32 v[170:171], v[88:89]
	v_mov_b64_e32 v[102:103], v[74:75]
	v_mov_b64_e32 v[106:107], v[78:79]
	v_mov_b64_e32 v[110:111], v[86:87]
	v_mov_b64_e32 v[90:91], v[82:83]
	v_mov_b64_e32 v[100:101], v[72:73]
	v_mov_b64_e32 v[104:105], v[76:77]
	v_mov_b64_e32 v[108:109], v[84:85]
	v_mov_b64_e32 v[88:89], v[80:81]
.LBB0_412:
	s_cmp_eq_u32 s64, 48
	s_cbranch_scc1 .LBB0_417
	s_waitcnt vmcnt(4)
	s_nop 1
	v_mfma_f32_16x16x32_bf16 v[114:117], v[44:47], v[24:27], 0
	v_mfma_f32_16x16x32_bf16 v[114:117], v[40:43], v[28:31], v[114:117]
	s_nop 7
	v_add_u32_e32 v43, s64, v200
	v_subrev_u32_e32 v40, 64, v43
	v_cmp_gt_u32_e32 vcc, s16, v40
	v_cmp_lt_i32_e64 s[44:45], -1, v112
	v_add_u32_e32 v41, 0xffffff40, v43
	s_and_b64 vcc, s[44:45], vcc
	v_cndmask_b32_e32 v40, v245, v114, vcc
	v_cmp_lt_u32_e32 vcc, s17, v41
	v_cmp_lt_i32_e64 s[44:45], -2, v112
	s_and_b64 vcc, s[44:45], vcc
	v_subrev_u32_e32 v42, 62, v43
	v_cndmask_b32_e32 v41, v245, v115, vcc
	v_cmp_gt_u32_e32 vcc, s16, v42
	v_cmp_lt_i32_e64 s[44:45], -3, v112
	s_and_b64 vcc, s[44:45], vcc
	v_subrev_u32_e32 v43, 61, v43
	v_cndmask_b32_e32 v42, v245, v116, vcc
	v_cmp_gt_u32_e32 vcc, s16, v43
	v_cmp_lt_i32_e64 s[44:45], -4, v112
	s_and_b64 vcc, s[44:45], vcc
	v_cndmask_b32_e32 v43, v245, v117, vcc
	v_max_f32_e32 v44, v43, v43
	v_max_f32_e32 v45, v42, v42
	v_max_f32_e32 v44, v45, v44
	v_max3_f32 v44, v40, v41, v44
	ds_swizzle_b32 v45, v44 offset:swizzle(SWAP,16)
	s_waitcnt lgkmcnt(0)
	v_max_f32_e32 v45, v45, v45
	v_max_f32_e32 v44, v44, v45
	v_mov_b32_e32 v45, v44
	s_nop 1
	v_permlane32_swap_b32_e32 v44, v45
	v_max_f32_e32 v45, v45, v45
	v_max_f32_e32 v44, v44, v44
	v_max_f32_e32 v44, v44, v45
	v_mul_f32_e32 v44, 0x3e38aa3b, v44
	v_add_f32_e32 v45, 0x41000000, v169
	v_cmp_gt_f32_e32 vcc, v44, v45
	s_cbranch_vccz .LBB0_415
	s_nop 0
	v_cndmask_b32_e32 v44, v169, v44, vcc
	v_sub_f32_e32 v45, v169, v44
	v_exp_f32_e32 v46, v45
	v_mov_b32_e32 v169, v44
	v_mul_f32_e32 v171, v171, v46
	v_pk_mul_f32 v[14:15], v[14:15], v[46:47] op_sel_hi:[1,0]
	v_pk_mul_f32 v[12:13], v[12:13], v[46:47] op_sel_hi:[1,0]
	v_pk_mul_f32 v[10:11], v[10:11], v[46:47] op_sel_hi:[1,0]
	v_pk_mul_f32 v[8:9], v[8:9], v[46:47] op_sel_hi:[1,0]
	v_pk_mul_f32 v[6:7], v[6:7], v[46:47] op_sel_hi:[1,0]
	v_pk_mul_f32 v[4:5], v[4:5], v[46:47] op_sel_hi:[1,0]
	v_pk_mul_f32 v[2:3], v[2:3], v[46:47] op_sel_hi:[1,0]
	v_pk_mul_f32 v[0:1], v[0:1], v[46:47] op_sel_hi:[1,0]
	s_branch .LBB0_416

.LBB0_416:
	v_fma_f32 v41, v41, s18, -v44
	v_fma_f32 v40, v40, s18, -v44
	v_exp_f32_e32 v46, v41
	v_fma_f32 v41, v42, s18, -v44
	v_fma_f32 v42, v43, s18, -v44
	v_exp_f32_e32 v40, v40
	v_exp_f32_e32 v41, v41
	v_exp_f32_e32 v47, v42
	s_nop 0
	v_pk_add_f32 v[42:43], v[40:41], v[46:47]
	s_nop 0
	v_add_f32_e32 v42, v42, v43
	v_pk_add_f32 v[42:43], v[170:171], v[42:43] op_sel_hi:[1,0]
	v_cvt_pk_bf16_f32 v40, v40, v46
	v_cvt_pk_bf16_f32 v41, v41, v47
	s_nop 0
	v_mov_b32_e32 v171, v43
	s_nop 1
	v_mfma_f32_16x16x16_bf16 v[12:15], v[56:57], v[40:41], v[12:15]
	v_mfma_f32_16x16x16_bf16 v[8:11], v[58:59], v[40:41], v[8:11]
	v_mfma_f32_16x16x16_bf16 v[4:7], v[60:61], v[40:41], v[4:7]
	v_mfma_f32_16x16x16_bf16 v[0:3], v[62:63], v[40:41], v[0:3]
	s_nop 7
.LBB0_417:
	s_cmp_gt_u32 s62, 6
	s_cselect_b64 s[38:39], -1, 0
	s_cmp_lt_u32 s62, 7
	s_cselect_b32 s44, s64, 0x90
	s_add_i32 s44, s44, s61
	s_waitcnt vmcnt(5)
	v_or_b32_e32 v40, s44, v149
	v_lshl_add_u32 v40, v40, 2, s8
	v_add_u32_e32 v41, s44, v194
	v_med3_i32 v40, v40, 0, v244
	v_lshl_add_u32 v41, v41, 2, s8
	v_med3_i32 v42, v41, 0, v244
	v_mul_u32_u24_e32 v176, 0x2800, v40
	v_lshl_add_u64 v[40:41], v[164:165], 0, v[176:177]
	v_mul_u32_u24_e32 v176, 0x2800, v42
	s_waitcnt lgkmcnt(1)
	v_lshl_add_u64 v[60:61], v[166:167], 0, v[176:177]
	global_load_dwordx4 v[44:47], v[40:41], off offset:2048
	s_nop 0
	global_load_dwordx4 v[40:43], v[40:41], off offset:2112
	s_nop 0
	global_load_dwordx4 v[56:59], v[60:61], off offset:3600
	s_waitcnt lgkmcnt(0)
	global_load_dwordx4 v[60:63], v[60:61], off offset:3584
	s_andn2_b64 vcc, exec, s[4:5]
	s_cbranch_vccnz .LBB0_423
	s_waitcnt vmcnt(8)
	ds_write_b128 v211, v[68:71]
	ds_write_b128 v211, v[64:67] offset:16
	ds_read_b64_tr_b16 v[64:65], v212
	ds_read_b64_tr_b16 v[66:67], v212 offset:32
	ds_read_b64_tr_b16 v[68:69], v212 offset:64
	ds_read_b64_tr_b16 v[70:71], v212 offset:96
	s_andn2_b64 vcc, exec, s[0:1]
	s_mov_b64 s[0:1], -1
	s_cbranch_vccnz .LBB0_420
	v_add_u32_e32 v173, s64, v200
	s_mov_b64 s[0:1], 0
.LBB0_420:
	v_add_u32_e32 v174, 0xffffff60, v172
	s_andn2_b64 vcc, exec, s[0:1]
	v_cmp_lt_i32_e64 s[50:51], -1, v174
	v_cmp_lt_i32_e64 s[48:49], -2, v174
	v_cmp_lt_i32_e64 s[46:47], -3, v174
	v_cmp_lt_i32_e64 s[44:45], -4, v174
	s_cbranch_vccnz .LBB0_424
	v_add_u32_e32 v173, s64, v200
	v_subrev_u32_e32 v89, 32, v173
	v_cmp_gt_u32_e32 vcc, s16, v89
	v_add_u32_e32 v88, 0xffffff60, v173
	s_and_b64 vcc, s[50:51], vcc
	s_nop 1
	v_mfma_f32_16x16x32_bf16 v[100:103], v[32:35], v[16:19], 0
	v_mfma_f32_16x16x32_bf16 v[100:103], v[36:39], v[20:23], v[100:103]
	s_nop 7
	s_nop 0
	v_cndmask_b32_e32 v90, v245, v100, vcc
	v_cmp_lt_u32_e32 vcc, s17, v88
	s_and_b64 vcc, s[48:49], vcc
	v_subrev_u32_e32 v88, 30, v173
	v_cndmask_b32_e32 v91, v245, v101, vcc
	v_cmp_gt_u32_e32 vcc, s16, v88
	s_and_b64 vcc, s[46:47], vcc
	v_subrev_u32_e32 v88, 29, v173
	v_cndmask_b32_e32 v100, v245, v102, vcc
	v_cmp_gt_u32_e32 vcc, s16, v88
	s_and_b64 vcc, s[44:45], vcc
	v_max_f32_e32 v89, v100, v100
	v_cndmask_b32_e32 v101, v245, v103, vcc
	v_max_f32_e32 v88, v101, v101
	v_max_f32_e32 v88, v89, v88
	v_max3_f32 v88, v90, v91, v88
	ds_swizzle_b32 v89, v88 offset:swizzle(SWAP,16)
	s_waitcnt lgkmcnt(0)
	v_max_f32_e32 v89, v89, v89
	v_max_f32_e32 v88, v88, v89
	v_mov_b32_e32 v89, v88
	s_nop 1
	v_permlane32_swap_b32_e32 v88, v89
	v_max_f32_e32 v89, v89, v89
	v_max_f32_e32 v88, v88, v88
	v_max_f32_e32 v88, v88, v89
	v_mul_f32_e32 v88, 0x3e38aa3b, v88
	v_add_f32_e32 v89, 0x41000000, v168
	v_cmp_gt_f32_e32 vcc, v88, v89
	s_cbranch_vccz .LBB0_425
	s_nop 0
	v_cndmask_b32_e32 v88, v168, v88, vcc
	v_sub_f32_e32 v89, v168, v88
	v_exp_f32_e32 v102, v89
	v_mov_b32_e32 v89, v169
	v_mov_b64_e32 v[168:169], v[88:89]
	v_mul_f32_e32 v170, v170, v102
	v_pk_mul_f32 v[86:87], v[86:87], v[102:103] op_sel_hi:[1,0]
	v_pk_mul_f32 v[84:85], v[84:85], v[102:103] op_sel_hi:[1,0]
	v_pk_mul_f32 v[82:83], v[82:83], v[102:103] op_sel_hi:[1,0]
	v_pk_mul_f32 v[80:81], v[80:81], v[102:103] op_sel_hi:[1,0]
	v_pk_mul_f32 v[78:79], v[78:79], v[102:103] op_sel_hi:[1,0]
	v_pk_mul_f32 v[76:77], v[76:77], v[102:103] op_sel_hi:[1,0]
	v_pk_mul_f32 v[74:75], v[74:75], v[102:103] op_sel_hi:[1,0]
	v_pk_mul_f32 v[72:73], v[72:73], v[102:103] op_sel_hi:[1,0]
	s_branch .LBB0_426

.LBB0_426:
	v_fma_f32 v89, v90, s18, -v88
	v_exp_f32_e32 v90, v89
	v_fma_f32 v89, v91, s18, -v88
	v_exp_f32_e32 v102, v89
	v_fma_f32 v89, v100, s18, -v88
	v_fma_f32 v88, v101, s18, -v88
	v_exp_f32_e32 v91, v89
	v_exp_f32_e32 v103, v88
	s_nop 0
	v_pk_add_f32 v[88:89], v[90:91], v[102:103]
	s_nop 0
	v_pk_add_f32 v[88:89], v[88:89], v[88:89] op_sel:[0,1] op_sel_hi:[1,0]
	v_cvt_pk_bf16_f32 v90, v90, v102
	v_cvt_pk_bf16_f32 v91, v91, v103
	s_nop 0
	v_pk_add_f32 v[88:89], v[170:171], v[88:89]
	s_nop 1
	v_mfma_f32_16x16x16_bf16 v[84:87], v[64:65], v[90:91], v[84:87]
	v_mfma_f32_16x16x16_bf16 v[80:83], v[66:67], v[90:91], v[80:83]
	v_mfma_f32_16x16x16_bf16 v[76:79], v[68:69], v[90:91], v[76:79]
	v_mfma_f32_16x16x16_bf16 v[72:75], v[70:71], v[90:91], v[72:75]
	s_nop 7
	s_nop 0
	v_mov_b32_e32 v89, v171
	v_mov_b64_e32 v[114:115], v[86:87]
	v_mov_b64_e32 v[118:119], v[82:83]
	v_mov_b64_e32 v[122:123], v[78:79]
	v_mov_b64_e32 v[126:127], v[74:75]
	v_mov_b64_e32 v[130:131], v[74:75]
	v_mov_b64_e32 v[134:135], v[78:79]
	v_mov_b64_e32 v[138:139], v[86:87]
	v_mov_b64_e32 v[142:143], v[82:83]
	v_mov_b64_e32 v[170:171], v[88:89]
	v_mov_b64_e32 v[112:113], v[84:85]
	v_mov_b64_e32 v[116:117], v[80:81]
	v_mov_b64_e32 v[120:121], v[76:77]
	v_mov_b64_e32 v[124:125], v[72:73]
	v_mov_b64_e32 v[128:129], v[72:73]
	v_mov_b64_e32 v[132:133], v[76:77]
	v_mov_b64_e32 v[136:137], v[84:85]
	v_mov_b64_e32 v[140:141], v[80:81]
.LBB0_427:
	s_nop 1
	v_mfma_f32_16x16x32_bf16 v[72:75], v[32:35], v[24:27], 0
	v_mfma_f32_16x16x32_bf16 v[72:75], v[36:39], v[28:31], v[72:75]
	s_nop 7
	v_subrev_u32_e32 v32, 48, v173
	v_cmp_gt_u32_e32 vcc, s16, v32
	v_cmp_lt_i32_e64 s[44:45], -1, v174
	v_add_u32_e32 v33, 0xffffff50, v173
	s_and_b64 vcc, s[44:45], vcc
	v_cndmask_b32_e32 v32, v245, v72, vcc
	v_cmp_lt_u32_e32 vcc, s17, v33
	v_cmp_lt_i32_e64 s[44:45], -2, v174
	s_and_b64 vcc, s[44:45], vcc
	v_subrev_u32_e32 v34, 46, v173
	v_cndmask_b32_e32 v33, v245, v73, vcc
	v_cmp_gt_u32_e32 vcc, s16, v34
	v_cmp_lt_i32_e64 s[44:45], -3, v174
	s_and_b64 vcc, s[44:45], vcc
	v_subrev_u32_e32 v35, 45, v173
	v_cndmask_b32_e32 v34, v245, v74, vcc
	v_cmp_gt_u32_e32 vcc, s16, v35
	v_cmp_lt_i32_e64 s[44:45], -4, v174
	s_and_b64 vcc, s[44:45], vcc
	v_cndmask_b32_e32 v35, v245, v75, vcc
	v_max_f32_e32 v36, v35, v35
	v_max_f32_e32 v37, v34, v34
	v_max_f32_e32 v36, v37, v36
	v_max3_f32 v36, v32, v33, v36
	ds_swizzle_b32 v37, v36 offset:swizzle(SWAP,16)
	s_waitcnt lgkmcnt(0)
	v_max_f32_e32 v37, v37, v37
	v_max_f32_e32 v36, v36, v37
	v_mov_b32_e32 v37, v36
	s_nop 1
	v_permlane32_swap_b32_e32 v36, v37
	v_max_f32_e32 v37, v37, v37
	v_max_f32_e32 v36, v36, v36
	v_max_f32_e32 v36, v36, v37
	v_mul_f32_e32 v36, 0x3e38aa3b, v36
	v_add_f32_e32 v37, 0x41000000, v169
	v_cmp_gt_f32_e32 vcc, v36, v37
	s_cbranch_vccz .LBB0_429
	s_nop 0
	v_cndmask_b32_e32 v36, v169, v36, vcc
	v_sub_f32_e32 v37, v169, v36
	v_exp_f32_e32 v38, v37
	v_mov_b32_e32 v169, v36
	v_mul_f32_e32 v171, v171, v38
	v_pk_mul_f32 v[14:15], v[14:15], v[38:39] op_sel_hi:[1,0]
	v_pk_mul_f32 v[12:13], v[12:13], v[38:39] op_sel_hi:[1,0]
	v_pk_mul_f32 v[10:11], v[10:11], v[38:39] op_sel_hi:[1,0]
	v_pk_mul_f32 v[8:9], v[8:9], v[38:39] op_sel_hi:[1,0]
	v_pk_mul_f32 v[6:7], v[6:7], v[38:39] op_sel_hi:[1,0]
	v_pk_mul_f32 v[4:5], v[4:5], v[38:39] op_sel_hi:[1,0]
	v_pk_mul_f32 v[2:3], v[2:3], v[38:39] op_sel_hi:[1,0]
	v_pk_mul_f32 v[0:1], v[0:1], v[38:39] op_sel_hi:[1,0]
	s_branch .LBB0_430

.LBB0_431:
	s_min_u32 s0, s62, 5
	s_lshl_b32 s0, s0, 4
	s_add_i32 s0, s63, s0
	v_or_b32_e32 v32, s0, v149
	v_lshl_add_u32 v32, v32, 2, s8
	v_add_u32_e32 v33, s0, v194
	v_med3_i32 v32, v32, 0, v244
	v_lshl_add_u32 v33, v33, 2, s8
	v_med3_i32 v33, v33, 0, v244
	v_mul_u32_u24_e32 v176, 0x2800, v32
	v_lshl_add_u64 v[36:37], v[164:165], 0, v[176:177]
	v_mul_u32_u24_e32 v176, 0x2800, v33
	s_waitcnt vmcnt(8)
	v_lshl_add_u64 v[68:69], v[166:167], 0, v[176:177]
	global_load_dwordx4 v[32:35], v[36:37], off offset:2048
	s_nop 0
	global_load_dwordx4 v[36:39], v[36:37], off offset:2112
	s_nop 0
	global_load_dwordx4 v[64:67], v[68:69], off offset:3600
	s_nop 0
	global_load_dwordx4 v[68:71], v[68:69], off offset:3584
	s_andn2_b64 vcc, exec, s[52:53]
	s_cbranch_vccnz .LBB0_406
	s_waitcnt vmcnt(8)
	ds_write_b128 v211, v[96:99]
	ds_write_b128 v211, v[92:95] offset:16
	ds_read_b64_tr_b16 v[92:93], v212
	ds_read_b64_tr_b16 v[94:95], v212 offset:32
	ds_read_b64_tr_b16 v[96:97], v212 offset:64
	ds_read_b64_tr_b16 v[98:99], v212 offset:96
	v_add_u32_e32 v176, 0xffffff70, v172
	s_mov_b64 s[0:1], -1
	s_cmpk_lg_i32 s64, 0xa0
	v_cmp_lt_i32_e64 s[48:49], -1, v176
	v_cmp_lt_i32_e64 s[46:47], -2, v176
	v_cmp_lt_i32_e64 s[44:45], -3, v176
	v_cmp_lt_i32_e32 vcc, -4, v176
	s_cbranch_scc0 .LBB0_436
	v_add_u32_e32 v214, s64, v200
	v_add_u32_e32 v73, -16, v214
	v_cmp_gt_u32_e64 s[50:51], s16, v73
	s_nop 1
	v_mfma_f32_16x16x32_bf16 v[74:77], v[48:51], v[16:19], 0
	v_mfma_f32_16x16x32_bf16 v[74:77], v[52:55], v[20:23], v[74:77]
	s_nop 7
	v_add_u32_e32 v72, 0xffffff70, v214
	s_and_b64 s[48:49], s[48:49], s[50:51]
	v_cndmask_b32_e64 v74, v245, v74, s[48:49]
	v_cmp_lt_u32_e64 s[48:49], s17, v72
	s_and_b64 s[46:47], s[46:47], s[48:49]
	v_add_u32_e32 v72, -14, v214
	v_cndmask_b32_e64 v75, v245, v75, s[46:47]
	v_cmp_gt_u32_e64 s[46:47], s16, v72
	s_and_b64 s[44:45], s[44:45], s[46:47]
	v_add_u32_e32 v72, -13, v214
	v_cndmask_b32_e64 v76, v245, v76, s[44:45]
	v_cmp_gt_u32_e64 s[44:45], s16, v72
	s_and_b64 vcc, vcc, s[44:45]
	v_cndmask_b32_e32 v77, v245, v77, vcc
	v_max_f32_e32 v72, v77, v77
	v_max_f32_e32 v73, v76, v76
	v_max_f32_e32 v72, v73, v72
	v_max3_f32 v72, v74, v75, v72
	ds_swizzle_b32 v73, v72 offset:swizzle(SWAP,16)
	v_mov_b64_e32 v[100:101], v[124:125]
	v_mov_b64_e32 v[104:105], v[120:121]
	v_mov_b64_e32 v[88:89], v[116:117]
	v_mov_b64_e32 v[108:109], v[112:113]
	s_waitcnt lgkmcnt(0)
	v_max_f32_e32 v73, v73, v73
	v_max_f32_e32 v72, v72, v73
	v_mov_b32_e32 v73, v72
	s_nop 1
	v_permlane32_swap_b32_e32 v72, v73
	v_max_f32_e32 v73, v73, v73
	v_max_f32_e32 v72, v72, v72
	v_max_f32_e32 v72, v72, v73
	v_mul_f32_e32 v79, 0x3e38aa3b, v72
	v_add_f32_e32 v72, 0x41000000, v168
	v_cmp_gt_f32_e32 vcc, v79, v72
	v_mov_b64_e32 v[102:103], v[126:127]
	v_mov_b64_e32 v[106:107], v[122:123]
	v_mov_b64_e32 v[90:91], v[118:119]
	v_mov_b64_e32 v[110:111], v[114:115]
	v_mov_b64_e32 v[72:73], v[170:171]
	v_mov_b64_e32 v[172:173], v[168:169]
	v_mov_b32_e32 v78, v168
	s_cbranch_vccz .LBB0_435
	v_cndmask_b32_e32 v172, v168, v79, vcc
	v_sub_f32_e32 v72, v168, v172
	v_exp_f32_e32 v78, v72
	v_mov_b32_e32 v173, v169
	v_mov_b32_e32 v73, v171
	v_mul_f32_e32 v72, v170, v78
	v_pk_mul_f32 v[110:111], v[114:115], v[78:79] op_sel_hi:[1,0]
	v_pk_mul_f32 v[108:109], v[112:113], v[78:79] op_sel_hi:[1,0]
	v_pk_mul_f32 v[90:91], v[118:119], v[78:79] op_sel_hi:[1,0]
	v_pk_mul_f32 v[88:89], v[116:117], v[78:79] op_sel_hi:[1,0]
	v_pk_mul_f32 v[106:107], v[122:123], v[78:79] op_sel_hi:[1,0]
	v_pk_mul_f32 v[104:105], v[120:121], v[78:79] op_sel_hi:[1,0]
	v_pk_mul_f32 v[102:103], v[126:127], v[78:79] op_sel_hi:[1,0]
	v_pk_mul_f32 v[100:101], v[124:125], v[78:79] op_sel_hi:[1,0]
	v_mov_b32_e32 v78, v172
.LBB0_435:
	v_fma_f32 v75, v75, s18, -v78
	v_fma_f32 v74, v74, s18, -v78
	v_exp_f32_e32 v80, v75
	v_fma_f32 v75, v76, s18, -v78
	v_fma_f32 v76, v77, s18, -v78
	v_exp_f32_e32 v74, v74
	v_exp_f32_e32 v75, v75
	v_exp_f32_e32 v81, v76
	s_mov_b64 s[0:1], 0
	v_pk_add_f32 v[76:77], v[74:75], v[80:81]
	s_nop 0
	v_pk_add_f32 v[76:77], v[76:77], v[76:77] op_sel:[0,1] op_sel_hi:[1,0]
	s_nop 0
	v_pk_add_f32 v[174:175], v[72:73], v[76:77]
	v_cvt_pk_bf16_f32 v72, v74, v80
	s_nop 0
	v_mov_b32_e32 v175, v73
	v_cvt_pk_bf16_f32 v73, v75, v81
	s_nop 0
	s_nop 1
	v_mfma_f32_16x16x16_bf16 v[108:111], v[92:93], v[72:73], v[108:111]
	v_mfma_f32_16x16x16_bf16 v[88:91], v[94:95], v[72:73], v[88:91]
	v_mfma_f32_16x16x16_bf16 v[104:107], v[96:97], v[72:73], v[104:107]
	v_mfma_f32_16x16x16_bf16 v[100:103], v[98:99], v[72:73], v[100:103]
	s_nop 7
.LBB0_436:
	s_nop 0
	v_mov_b64_e32 v[72:73], v[100:101]
	v_mov_b64_e32 v[76:77], v[104:105]
	v_mov_b64_e32 v[80:81], v[88:89]
	v_mov_b64_e32 v[84:85], v[108:109]
	s_and_b64 vcc, exec, s[0:1]
	v_mov_b64_e32 v[74:75], v[102:103]
	v_mov_b64_e32 v[78:79], v[106:107]
	v_mov_b64_e32 v[82:83], v[90:91]
	v_mov_b64_e32 v[86:87], v[110:111]
	s_cbranch_vccz .LBB0_438
	v_mov_b64_e32 v[88:89], v[140:141]
	v_mov_b64_e32 v[108:109], v[136:137]
	v_mov_b64_e32 v[104:105], v[132:133]
	v_mov_b64_e32 v[100:101], v[128:129]
	v_mov_b64_e32 v[72:73], v[124:125]
	v_mov_b64_e32 v[76:77], v[120:121]
	v_mov_b64_e32 v[80:81], v[116:117]
	v_mov_b64_e32 v[84:85], v[112:113]
	v_mov_b32_e32 v214, v213
	v_mov_b64_e32 v[90:91], v[142:143]
	v_mov_b64_e32 v[110:111], v[138:139]
	v_mov_b64_e32 v[106:107], v[134:135]
	v_mov_b64_e32 v[102:103], v[130:131]
	v_mov_b64_e32 v[74:75], v[126:127]
	v_mov_b64_e32 v[78:79], v[122:123]
	v_mov_b64_e32 v[82:83], v[118:119]
	v_mov_b64_e32 v[86:87], v[114:115]
	v_mov_b64_e32 v[174:175], v[170:171]
	v_mov_b64_e32 v[172:173], v[168:169]
.LBB0_438:
	s_nop 1
	v_mfma_f32_16x16x32_bf16 v[112:115], v[48:51], v[24:27], 0
	v_mfma_f32_16x16x32_bf16 v[112:115], v[52:55], v[28:31], v[112:115]
	s_nop 7
	v_subrev_u32_e32 v48, 32, v214
	v_cmp_gt_u32_e32 vcc, s16, v48
	v_cmp_lt_i32_e64 s[44:45], -1, v176
	v_add_u32_e32 v49, 0xffffff60, v214
	s_and_b64 vcc, s[44:45], vcc
	v_cndmask_b32_e32 v48, v245, v112, vcc
	v_cmp_lt_u32_e32 vcc, s17, v49
	v_cmp_lt_i32_e64 s[44:45], -2, v176
	s_and_b64 vcc, s[44:45], vcc
	v_subrev_u32_e32 v50, 30, v214
	v_cndmask_b32_e32 v49, v245, v113, vcc
	v_cmp_gt_u32_e32 vcc, s16, v50
	v_cmp_lt_i32_e64 s[44:45], -3, v176
	s_and_b64 vcc, s[44:45], vcc
	v_subrev_u32_e32 v51, 29, v214
	v_cndmask_b32_e32 v50, v245, v114, vcc
	v_cmp_gt_u32_e32 vcc, s16, v51
	v_cmp_lt_i32_e64 s[44:45], -4, v176
	s_and_b64 vcc, s[44:45], vcc
	v_cndmask_b32_e32 v51, v245, v115, vcc
	v_max_f32_e32 v52, v51, v51
	v_max_f32_e32 v53, v50, v50
	v_max_f32_e32 v52, v53, v52
	v_max3_f32 v52, v48, v49, v52
	ds_swizzle_b32 v53, v52 offset:swizzle(SWAP,16)
	s_waitcnt lgkmcnt(0)
	v_max_f32_e32 v53, v53, v53
	v_max_f32_e32 v52, v52, v53
	v_mov_b32_e32 v53, v52
	s_nop 1
	v_permlane32_swap_b32_e32 v52, v53
	v_max_f32_e32 v53, v53, v53
	v_max_f32_e32 v52, v52, v52
	v_max_f32_e32 v52, v52, v53
	v_mul_f32_e32 v52, 0x3e38aa3b, v52
	v_add_f32_e32 v53, 0x41000000, v173
	v_cmp_gt_f32_e32 vcc, v52, v53
	s_cbranch_vccz .LBB0_440
	s_nop 0
	v_cndmask_b32_e32 v52, v173, v52, vcc
	v_sub_f32_e32 v53, v173, v52
	v_exp_f32_e32 v54, v53
	v_mov_b32_e32 v173, v52
	v_mul_f32_e32 v175, v175, v54
	v_pk_mul_f32 v[14:15], v[14:15], v[54:55] op_sel_hi:[1,0]
	v_pk_mul_f32 v[12:13], v[12:13], v[54:55] op_sel_hi:[1,0]
	v_pk_mul_f32 v[10:11], v[10:11], v[54:55] op_sel_hi:[1,0]
	v_pk_mul_f32 v[8:9], v[8:9], v[54:55] op_sel_hi:[1,0]
	v_pk_mul_f32 v[6:7], v[6:7], v[54:55] op_sel_hi:[1,0]
	v_pk_mul_f32 v[4:5], v[4:5], v[54:55] op_sel_hi:[1,0]
	v_pk_mul_f32 v[2:3], v[2:3], v[54:55] op_sel_hi:[1,0]
	v_pk_mul_f32 v[0:1], v[0:1], v[54:55] op_sel_hi:[1,0]
	s_branch .LBB0_441

.LBB0_441:
	v_fma_f32 v49, v49, s18, -v52
	v_fma_f32 v48, v48, s18, -v52
	v_exp_f32_e32 v54, v49
	v_fma_f32 v49, v50, s18, -v52
	v_fma_f32 v50, v51, s18, -v52
	v_exp_f32_e32 v48, v48
	v_exp_f32_e32 v49, v49
	v_exp_f32_e32 v55, v50
	v_mov_b64_e32 v[168:169], v[172:173]
	v_pk_add_f32 v[50:51], v[48:49], v[54:55]
	s_nop 0
	v_add_f32_e32 v50, v50, v51
	v_pk_add_f32 v[50:51], v[174:175], v[50:51] op_sel_hi:[1,0]
	v_cvt_pk_bf16_f32 v48, v48, v54
	v_cvt_pk_bf16_f32 v49, v49, v55
	s_nop 0
	v_mov_b32_e32 v175, v51
	v_mov_b64_e32 v[170:171], v[174:175]
	s_nop 1
	v_mfma_f32_16x16x16_bf16 v[12:15], v[92:93], v[48:49], v[12:15]
	v_mfma_f32_16x16x16_bf16 v[8:11], v[94:95], v[48:49], v[8:11]
	v_mfma_f32_16x16x16_bf16 v[4:7], v[96:97], v[48:49], v[4:7]
	v_mfma_f32_16x16x16_bf16 v[0:3], v[98:99], v[48:49], v[0:3]
	s_nop 7
	s_add_i32 s62, s62, 3
	s_add_i32 s64, s64, 48
	s_and_b64 vcc, exec, s[38:39]
	s_cbranch_vccz .LBB0_407

.LBB0_447:
	v_fmamk_f32 v53, v53, 0x3e38aa3b, v86
	v_fmamk_f32 v52, v52, 0x3e38aa3b, v86
	v_exp_f32_e32 v56, v53
	v_fmamk_f32 v53, v54, 0x3e38aa3b, v86
	v_fmac_f32_e32 v86, 0x3e38aa3b, v55
	v_exp_f32_e32 v52, v52
	v_exp_f32_e32 v53, v53
	v_exp_f32_e32 v57, v86
	s_add_i32 s46, s46, 3
	s_andn2_b64 vcc, exec, s[0:1]
	s_add_i32 s39, s39, 48
	v_pk_add_f32 v[54:55], v[52:53], v[56:57]
	v_cvt_pk_bf16_f32 v52, v52, v56
	v_cvt_pk_bf16_f32 v53, v53, v57
	s_nop 0
	v_add_f32_e32 v54, v54, v55
	v_add_f32_e32 v86, v87, v54
	s_nop 1
	v_mfma_f32_16x16x16_bf16 v[48:51], v[60:61], v[52:53], v[48:51]
	v_mfma_f32_16x16x16_bf16 v[12:15], v[62:63], v[52:53], v[12:15]
	v_mfma_f32_16x16x16_bf16 v[68:71], v[64:65], v[52:53], v[68:71]
	v_mfma_f32_16x16x16_bf16 v[8:11], v[66:67], v[52:53], v[8:11]
	s_nop 7
	s_cbranch_vccz .LBB0_455
.LBB0_448:
	s_add_i32 s47, s4, s39
	s_add_i32 s0, s47, 0xa0
	s_cmp_lt_u32 s46, 7
	s_cselect_b32 s0, s0, 0x80
	s_add_i32 s0, s0, s5
	v_or_b32_e32 v52, s0, v149
	v_lshl_add_u32 v52, v52, 4, s9
	v_add_u32_e32 v53, s0, v194
	v_med3_i32 v52, v52, 0, v244
	v_lshl_add_u32 v53, v53, 4, s9
	v_med3_i32 v53, v53, 0, v244
	v_mul_u32_u24_e32 v176, 0x2800, v52
	v_lshl_add_u64 v[56:57], v[72:73], 0, v[176:177]
	v_mul_u32_u24_e32 v176, 0x2800, v53
	v_lshl_add_u64 v[64:65], v[74:75], 0, v[176:177]
	global_load_dwordx4 v[52:55], v[56:57], off offset:2560
	s_nop 0
	global_load_dwordx4 v[56:59], v[56:57], off offset:2624
	s_nop 0
	global_load_dwordx4 v[60:63], v[64:65], off offset:16
	s_nop 0
	global_load_dwordx4 v[64:67], v[64:65], off
	s_waitcnt vmcnt(6)
	ds_write_b128 v211, v[28:31]
	ds_write_b128 v211, v[16:19] offset:16
	v_add_u32_e32 v83, s39, v78
	ds_read_b64_tr_b16 v[16:17], v212
	ds_read_b64_tr_b16 v[18:19], v212 offset:32
	ds_read_b64_tr_b16 v[28:29], v212 offset:64
	ds_read_b64_tr_b16 v[30:31], v212 offset:96
	v_add_u32_e32 v84, s39, v195
	s_waitcnt vmcnt(4)
	s_nop 1
	v_mfma_f32_16x16x32_bf16 v[88:91], v[20:23], v[0:3], 0
	v_mfma_f32_16x16x32_bf16 v[88:91], v[24:27], v[4:7], v[88:91]
	s_nop 7
	v_add_u32_e32 v20, 0x80, v83
	v_cmp_gt_u32_e32 vcc, s16, v20
	v_cmp_lt_i32_e64 s[44:45], -1, v84
	s_and_b64 vcc, s[44:45], vcc
	v_cndmask_b32_e32 v20, v245, v88, vcc
	v_cmp_lt_u32_e32 vcc, s17, v83
	v_cmp_lt_i32_e64 s[44:45], -2, v84
	s_and_b64 vcc, s[44:45], vcc
	v_add_u32_e32 v22, 0x82, v83
	v_cndmask_b32_e32 v21, v245, v89, vcc
	v_cmp_gt_u32_e32 vcc, s16, v22
	v_cmp_lt_i32_e64 s[44:45], -3, v84
	s_and_b64 vcc, s[44:45], vcc
	v_add_u32_e32 v23, 0x83, v83
	v_cndmask_b32_e32 v22, v245, v90, vcc
	v_cmp_gt_u32_e32 vcc, s16, v23
	v_cmp_lt_i32_e64 s[44:45], -4, v84
	s_and_b64 vcc, s[44:45], vcc
	v_cndmask_b32_e32 v23, v245, v91, vcc
	v_max_f32_e32 v24, v23, v23
	v_max_f32_e32 v25, v22, v22
	v_max_f32_e32 v24, v25, v24
	v_max3_f32 v24, v20, v21, v24
	ds_swizzle_b32 v25, v24 offset:swizzle(SWAP,16)
	v_add_f32_e32 v85, 0x41000000, v82
	s_waitcnt lgkmcnt(0)
	v_max_f32_e32 v25, v25, v25
	v_max_f32_e32 v24, v24, v25
	v_mov_b32_e32 v25, v24
	s_nop 1
	v_permlane32_swap_b32_e32 v24, v25
	v_max_f32_e32 v25, v25, v25
	v_max_f32_e32 v24, v24, v24
	v_max_f32_e32 v24, v24, v25
	v_mul_f32_e32 v24, 0x3e38aa3b, v24
	v_cmp_gt_f32_e32 vcc, v24, v85
	s_cbranch_vccz .LBB0_450
	s_nop 0
	v_cndmask_b32_e32 v25, v82, v24, vcc
	v_sub_f32_e32 v24, v82, v25
	v_exp_f32_e32 v24, v24
	v_add_f32_e32 v85, 0x41000000, v25
	v_mov_b32_e32 v82, v25
	v_mul_f32_e32 v86, v86, v24
	v_pk_mul_f32 v[10:11], v[10:11], v[24:25] op_sel_hi:[1,0]
	v_pk_mul_f32 v[8:9], v[8:9], v[24:25] op_sel_hi:[1,0]
	v_pk_mul_f32 v[70:71], v[70:71], v[24:25] op_sel_hi:[1,0]
	v_pk_mul_f32 v[68:69], v[68:69], v[24:25] op_sel_hi:[1,0]
	v_pk_mul_f32 v[14:15], v[14:15], v[24:25] op_sel_hi:[1,0]
	v_pk_mul_f32 v[12:13], v[12:13], v[24:25] op_sel_hi:[1,0]
	v_pk_mul_f32 v[50:51], v[50:51], v[24:25] op_sel_hi:[1,0]
	v_pk_mul_f32 v[48:49], v[48:49], v[24:25] op_sel_hi:[1,0]
.LBB0_450:
	v_fma_f32 v21, v21, s18, -v82
	v_fma_f32 v20, v20, s18, -v82
	v_exp_f32_e32 v24, v21
	v_fma_f32 v21, v22, s18, -v82
	v_fma_f32 v22, v23, s18, -v82
	s_cmp_gt_u32 s46, 5
	v_exp_f32_e32 v20, v20
	v_exp_f32_e32 v21, v21
	v_exp_f32_e32 v25, v22
	s_cselect_b64 s[0:1], -1, 0
	s_addk_i32 s47, 0xb0
	s_cmp_lt_u32 s46, 6
	s_cselect_b32 s44, s47, 0x80
	s_add_i32 s44, s44, s5
	v_pk_add_f32 v[22:23], v[20:21], v[24:25]
	v_cvt_pk_bf16_f32 v20, v20, v24
	v_cvt_pk_bf16_f32 v21, v21, v25
	s_nop 0
	s_nop 1
	v_mfma_f32_16x16x16_bf16 v[48:51], v[16:17], v[20:21], v[48:51]
	v_mfma_f32_16x16x16_bf16 v[12:15], v[18:19], v[20:21], v[12:15]
	v_mfma_f32_16x16x16_bf16 v[68:71], v[28:29], v[20:21], v[68:71]
	v_mfma_f32_16x16x16_bf16 v[8:11], v[30:31], v[20:21], v[8:11]
	s_nop 7
	v_or_b32_e32 v16, s44, v149
	v_lshl_add_u32 v16, v16, 4, s9
	v_add_u32_e32 v17, s44, v194
	v_med3_i32 v16, v16, 0, v244
	v_lshl_add_u32 v17, v17, 4, s9
	v_med3_i32 v18, v17, 0, v244
	v_mul_u32_u24_e32 v176, 0x2800, v16
	v_lshl_add_u64 v[16:17], v[72:73], 0, v[176:177]
	v_mul_u32_u24_e32 v176, 0x2800, v18
	v_add_f32_e32 v22, v22, v23
	v_lshl_add_u64 v[28:29], v[74:75], 0, v[176:177]
	v_add_f32_e32 v87, v86, v22
	global_load_dwordx4 v[20:23], v[16:17], off offset:2560
	global_load_dwordx4 v[24:27], v[16:17], off offset:2624
	s_nop 0
	global_load_dwordx4 v[16:19], v[28:29], off offset:16
	s_nop 0
	global_load_dwordx4 v[28:31], v[28:29], off
	ds_write_b128 v211, v[36:39]
	ds_write_b128 v211, v[32:35] offset:16
	ds_read_b64_tr_b16 v[32:33], v212
	ds_read_b64_tr_b16 v[34:35], v212 offset:32
	ds_read_b64_tr_b16 v[36:37], v212 offset:64
	ds_read_b64_tr_b16 v[38:39], v212 offset:96
	v_add_u32_e32 v86, 16, v84
	s_nop 1
	v_mfma_f32_16x16x32_bf16 v[88:91], v[40:43], v[0:3], 0
	v_mfma_f32_16x16x32_bf16 v[88:91], v[44:47], v[4:7], v[88:91]
	s_nop 7
	v_add_u32_e32 v40, 0x90, v83
	v_cmp_gt_u32_e32 vcc, s16, v40
	v_cmp_lt_i32_e64 s[44:45], -1, v86
	v_add_u32_e32 v41, 16, v83
	s_and_b64 vcc, s[44:45], vcc
	v_cndmask_b32_e32 v40, v245, v88, vcc
	v_cmp_lt_u32_e32 vcc, s17, v41
	v_cmp_lt_i32_e64 s[44:45], -2, v86
	s_and_b64 vcc, s[44:45], vcc
	v_add_u32_e32 v42, 0x92, v83
	v_cndmask_b32_e32 v41, v245, v89, vcc
	v_cmp_gt_u32_e32 vcc, s16, v42
	v_cmp_lt_i32_e64 s[44:45], -3, v86
	s_and_b64 vcc, s[44:45], vcc
	v_add_u32_e32 v43, 0x93, v83
	v_cndmask_b32_e32 v42, v245, v90, vcc
	v_cmp_gt_u32_e32 vcc, s16, v43
	v_cmp_lt_i32_e64 s[44:45], -4, v86
	s_and_b64 vcc, s[44:45], vcc
	v_cndmask_b32_e32 v43, v245, v91, vcc
	v_max_f32_e32 v44, v43, v43
	v_max_f32_e32 v45, v42, v42
	v_max_f32_e32 v44, v45, v44
	v_max3_f32 v44, v40, v41, v44
	ds_swizzle_b32 v45, v44 offset:swizzle(SWAP,16)
	s_waitcnt lgkmcnt(0)
	v_max_f32_e32 v45, v45, v45
	v_max_f32_e32 v44, v44, v45
	v_mov_b32_e32 v45, v44
	s_nop 1
	v_permlane32_swap_b32_e32 v44, v45
	v_max_f32_e32 v45, v45, v45
	v_max_f32_e32 v44, v44, v44
	v_max_f32_e32 v44, v44, v45
	v_mul_f32_e32 v44, 0x3e38aa3b, v44
	v_cmp_gt_f32_e32 vcc, v44, v85
	s_cbranch_vccz .LBB0_452
	s_nop 0
	v_cndmask_b32_e32 v45, v82, v44, vcc
	v_sub_f32_e32 v44, v82, v45
	v_exp_f32_e32 v44, v44
	v_xor_b32_e32 v86, 0x80000000, v45
	v_add_f32_e32 v85, 0x41000000, v45
	v_mov_b32_e32 v82, v45
	v_mul_f32_e32 v87, v87, v44
	v_pk_mul_f32 v[50:51], v[50:51], v[44:45] op_sel_hi:[1,0]
	v_pk_mul_f32 v[48:49], v[48:49], v[44:45] op_sel_hi:[1,0]
	v_pk_mul_f32 v[14:15], v[14:15], v[44:45] op_sel_hi:[1,0]
	v_pk_mul_f32 v[12:13], v[12:13], v[44:45] op_sel_hi:[1,0]
	v_pk_mul_f32 v[70:71], v[70:71], v[44:45] op_sel_hi:[1,0]
	v_pk_mul_f32 v[68:69], v[68:69], v[44:45] op_sel_hi:[1,0]
	v_pk_mul_f32 v[10:11], v[10:11], v[44:45] op_sel_hi:[1,0]
	v_pk_mul_f32 v[8:9], v[8:9], v[44:45] op_sel_hi:[1,0]
	s_branch .LBB0_453

.LBB0_453:
	v_fmamk_f32 v41, v41, 0x3e38aa3b, v86
	v_fmamk_f32 v40, v40, 0x3e38aa3b, v86
	v_exp_f32_e32 v44, v41
	v_fmamk_f32 v41, v42, 0x3e38aa3b, v86
	v_fmamk_f32 v42, v43, 0x3e38aa3b, v86
	v_exp_f32_e32 v40, v40
	v_exp_f32_e32 v41, v41
	v_exp_f32_e32 v45, v42
	s_min_u32 s44, s46, 4
	s_lshl_b32 s44, s44, 4
	s_add_i32 s44, s44, s37
	v_pk_add_f32 v[42:43], v[40:41], v[44:45]
	v_cvt_pk_bf16_f32 v40, v40, v44
	v_cvt_pk_bf16_f32 v41, v41, v45
	v_add_u32_e32 v84, 32, v84
	s_nop 1
	v_mfma_f32_16x16x16_bf16 v[48:51], v[32:33], v[40:41], v[48:51]
	v_mfma_f32_16x16x16_bf16 v[12:15], v[34:35], v[40:41], v[12:15]
	v_mfma_f32_16x16x16_bf16 v[68:71], v[36:37], v[40:41], v[68:71]
	v_mfma_f32_16x16x16_bf16 v[8:11], v[38:39], v[40:41], v[8:11]
	s_nop 7
	v_or_b32_e32 v32, s44, v149
	v_lshl_add_u32 v32, v32, 4, s9
	v_add_u32_e32 v33, s44, v194
	v_med3_i32 v32, v32, 0, v244
	v_lshl_add_u32 v33, v33, 4, s9
	v_med3_i32 v34, v33, 0, v244
	v_mul_u32_u24_e32 v176, 0x2800, v32
	v_lshl_add_u64 v[32:33], v[72:73], 0, v[176:177]
	v_mul_u32_u24_e32 v176, 0x2800, v34
	v_add_f32_e32 v42, v42, v43
	v_lshl_add_u64 v[36:37], v[74:75], 0, v[176:177]
	v_add_f32_e32 v87, v87, v42
	global_load_dwordx4 v[40:43], v[32:33], off offset:2560
	global_load_dwordx4 v[44:47], v[32:33], off offset:2624
	s_nop 0
	global_load_dwordx4 v[32:35], v[36:37], off offset:16
	s_nop 0
	global_load_dwordx4 v[36:39], v[36:37], off
	s_waitcnt vmcnt(8)
	ds_write_b128 v211, v[64:67]
	ds_write_b128 v211, v[60:63] offset:16
	ds_read_b64_tr_b16 v[60:61], v212
	ds_read_b64_tr_b16 v[62:63], v212 offset:32
	ds_read_b64_tr_b16 v[64:65], v212 offset:64
	ds_read_b64_tr_b16 v[66:67], v212 offset:96
	s_nop 1
	v_mfma_f32_16x16x32_bf16 v[88:91], v[52:55], v[0:3], 0
	v_mfma_f32_16x16x32_bf16 v[88:91], v[56:59], v[4:7], v[88:91]
	s_nop 7
	v_add_u32_e32 v52, 0xa0, v83
	v_cmp_gt_u32_e32 vcc, s16, v52
	v_cmp_lt_i32_e64 s[44:45], -1, v84
	v_add_u32_e32 v53, 32, v83
	s_and_b64 vcc, s[44:45], vcc
	v_cndmask_b32_e32 v52, v245, v88, vcc
	v_cmp_lt_u32_e32 vcc, s17, v53
	v_cmp_lt_i32_e64 s[44:45], -2, v84
	s_and_b64 vcc, s[44:45], vcc
	v_add_u32_e32 v54, 0xa2, v83
	v_cndmask_b32_e32 v53, v245, v89, vcc
	v_cmp_gt_u32_e32 vcc, s16, v54
	v_cmp_lt_i32_e64 s[44:45], -3, v84
	s_and_b64 vcc, s[44:45], vcc
	v_add_u32_e32 v55, 0xa3, v83
	v_cndmask_b32_e32 v54, v245, v90, vcc
	v_cmp_gt_u32_e32 vcc, s16, v55
	v_cmp_lt_i32_e64 s[44:45], -4, v84
	s_and_b64 vcc, s[44:45], vcc
	v_cndmask_b32_e32 v55, v245, v91, vcc
	v_max_f32_e32 v56, v55, v55
	v_max_f32_e32 v57, v54, v54
	v_max_f32_e32 v56, v57, v56
	v_max3_f32 v56, v52, v53, v56
	ds_swizzle_b32 v57, v56 offset:swizzle(SWAP,16)
	s_waitcnt lgkmcnt(0)
	v_max_f32_e32 v57, v57, v57
	v_max_f32_e32 v56, v56, v57
	v_mov_b32_e32 v57, v56
	s_nop 1
	v_permlane32_swap_b32_e32 v56, v57
	v_max_f32_e32 v57, v57, v57
	v_max_f32_e32 v56, v56, v56
	v_max_f32_e32 v56, v56, v57
	v_mul_f32_e32 v56, 0x3e38aa3b, v56
	v_cmp_gt_f32_e32 vcc, v56, v85
	s_cbranch_vccz .LBB0_447
	s_nop 0
	v_cndmask_b32_e32 v57, v82, v56, vcc
	v_sub_f32_e32 v56, v82, v57
	v_exp_f32_e32 v56, v56
	v_xor_b32_e32 v86, 0x80000000, v57
	v_mov_b32_e32 v82, v57
	v_mul_f32_e32 v87, v87, v56
	v_pk_mul_f32 v[50:51], v[50:51], v[56:57] op_sel_hi:[1,0]
	v_pk_mul_f32 v[48:49], v[48:49], v[56:57] op_sel_hi:[1,0]
	v_pk_mul_f32 v[14:15], v[14:15], v[56:57] op_sel_hi:[1,0]
	v_pk_mul_f32 v[12:13], v[12:13], v[56:57] op_sel_hi:[1,0]
	v_pk_mul_f32 v[70:71], v[70:71], v[56:57] op_sel_hi:[1,0]
	v_pk_mul_f32 v[68:69], v[68:69], v[56:57] op_sel_hi:[1,0]
	v_pk_mul_f32 v[10:11], v[10:11], v[56:57] op_sel_hi:[1,0]
	v_pk_mul_f32 v[8:9], v[8:9], v[56:57] op_sel_hi:[1,0]
	s_branch .LBB0_447

.LBB0_458:
	v_fmamk_f32 v53, v53, 0x3e38aa3b, v81
	v_fmamk_f32 v52, v52, 0x3e38aa3b, v81
	v_exp_f32_e32 v56, v53
	v_fmamk_f32 v53, v54, 0x3e38aa3b, v81
	v_fmac_f32_e32 v81, 0x3e38aa3b, v55
	v_exp_f32_e32 v52, v52
	v_exp_f32_e32 v53, v53
	v_exp_f32_e32 v57, v81
	s_add_i32 s36, s36, 3
	s_andn2_b64 vcc, exec, s[0:1]
	s_add_i32 s30, s30, 48
	v_pk_add_f32 v[54:55], v[52:53], v[56:57]
	v_cvt_pk_bf16_f32 v52, v52, v56
	v_cvt_pk_bf16_f32 v53, v53, v57
	s_nop 0
	v_add_f32_e32 v54, v54, v55
	v_add_f32_e32 v81, v82, v54
	s_nop 1
	v_mfma_f32_16x16x16_bf16 v[48:51], v[60:61], v[52:53], v[48:51]
	v_mfma_f32_16x16x16_bf16 v[68:71], v[62:63], v[52:53], v[68:71]
	v_mfma_f32_16x16x16_bf16 v[12:15], v[64:65], v[52:53], v[12:15]
	v_mfma_f32_16x16x16_bf16 v[8:11], v[66:67], v[52:53], v[8:11]
	s_nop 7
	s_cbranch_vccz .LBB0_466
.LBB0_459:
	s_add_i32 s31, s4, s30
	s_add_i32 s0, s31, 0xa0
	s_cmp_lt_u32 s36, 7
	s_cselect_b32 s0, s0, 0x80
	s_add_i32 s0, s0, s5
	v_or_b32_e32 v52, s0, v149
	v_lshl_add_u32 v52, v52, 4, s10
	v_add_u32_e32 v53, s0, v194
	v_med3_i32 v52, v52, 0, v244
	v_lshl_add_u32 v53, v53, 4, s10
	v_med3_i32 v53, v53, 0, v244
	v_mul_u32_u24_e32 v176, 0x2800, v52
	v_lshl_add_u64 v[56:57], v[72:73], 0, v[176:177]
	v_mul_u32_u24_e32 v176, 0x2800, v53
	v_lshl_add_u64 v[64:65], v[74:75], 0, v[176:177]
	global_load_dwordx4 v[52:55], v[56:57], off offset:2560
	s_nop 0
	global_load_dwordx4 v[56:59], v[56:57], off offset:2624
	s_nop 0
	global_load_dwordx4 v[60:63], v[64:65], off offset:16
	s_nop 0
	global_load_dwordx4 v[64:67], v[64:65], off
	s_waitcnt vmcnt(6)
	ds_write_b128 v211, v[28:31]
	ds_write_b128 v211, v[16:19] offset:16
	v_add_u32_e32 v77, s30, v78
	ds_read_b64_tr_b16 v[16:17], v212
	ds_read_b64_tr_b16 v[18:19], v212 offset:32
	ds_read_b64_tr_b16 v[28:29], v212 offset:64
	ds_read_b64_tr_b16 v[30:31], v212 offset:96
	v_add_u32_e32 v79, s30, v195
	s_waitcnt vmcnt(4)
	s_nop 1
	v_mfma_f32_16x16x32_bf16 v[82:85], v[20:23], v[0:3], 0
	v_mfma_f32_16x16x32_bf16 v[82:85], v[24:27], v[4:7], v[82:85]
	s_nop 7
	v_add_u32_e32 v20, 0x80, v77
	v_cmp_gt_u32_e32 vcc, s16, v20
	v_cmp_lt_i32_e64 s[44:45], -1, v79
	s_and_b64 vcc, s[44:45], vcc
	v_cndmask_b32_e32 v20, v245, v82, vcc
	v_cmp_lt_u32_e32 vcc, s17, v77
	v_cmp_lt_i32_e64 s[44:45], -2, v79
	s_and_b64 vcc, s[44:45], vcc
	v_add_u32_e32 v22, 0x82, v77
	v_cndmask_b32_e32 v21, v245, v83, vcc
	v_cmp_gt_u32_e32 vcc, s16, v22
	v_cmp_lt_i32_e64 s[44:45], -3, v79
	s_and_b64 vcc, s[44:45], vcc
	v_add_u32_e32 v23, 0x83, v77
	v_cndmask_b32_e32 v22, v245, v84, vcc
	v_cmp_gt_u32_e32 vcc, s16, v23
	v_cmp_lt_i32_e64 s[44:45], -4, v79
	s_and_b64 vcc, s[44:45], vcc
	v_cndmask_b32_e32 v23, v245, v85, vcc
	v_max_f32_e32 v24, v23, v23
	v_max_f32_e32 v25, v22, v22
	v_max_f32_e32 v24, v25, v24
	v_max3_f32 v24, v20, v21, v24
	ds_swizzle_b32 v25, v24 offset:swizzle(SWAP,16)
	v_add_f32_e32 v80, 0x41000000, v76
	s_waitcnt lgkmcnt(0)
	v_max_f32_e32 v25, v25, v25
	v_max_f32_e32 v24, v24, v25
	v_mov_b32_e32 v25, v24
	s_nop 1
	v_permlane32_swap_b32_e32 v24, v25
	v_max_f32_e32 v25, v25, v25
	v_max_f32_e32 v24, v24, v24
	v_max_f32_e32 v24, v24, v25
	v_mul_f32_e32 v24, 0x3e38aa3b, v24
	v_cmp_gt_f32_e32 vcc, v24, v80
	s_cbranch_vccz .LBB0_461
	s_nop 0
	v_cndmask_b32_e32 v25, v76, v24, vcc
	v_sub_f32_e32 v24, v76, v25
	v_exp_f32_e32 v24, v24
	v_add_f32_e32 v80, 0x41000000, v25
	v_mov_b32_e32 v76, v25
	v_mul_f32_e32 v81, v81, v24
	v_pk_mul_f32 v[10:11], v[10:11], v[24:25] op_sel_hi:[1,0]
	v_pk_mul_f32 v[8:9], v[8:9], v[24:25] op_sel_hi:[1,0]
	v_pk_mul_f32 v[14:15], v[14:15], v[24:25] op_sel_hi:[1,0]
	v_pk_mul_f32 v[12:13], v[12:13], v[24:25] op_sel_hi:[1,0]
	v_pk_mul_f32 v[70:71], v[70:71], v[24:25] op_sel_hi:[1,0]
	v_pk_mul_f32 v[68:69], v[68:69], v[24:25] op_sel_hi:[1,0]
	v_pk_mul_f32 v[50:51], v[50:51], v[24:25] op_sel_hi:[1,0]
	v_pk_mul_f32 v[48:49], v[48:49], v[24:25] op_sel_hi:[1,0]
.LBB0_461:
	v_fma_f32 v21, v21, s18, -v76
	v_fma_f32 v20, v20, s18, -v76
	v_exp_f32_e32 v24, v21
	v_fma_f32 v21, v22, s18, -v76
	v_fma_f32 v22, v23, s18, -v76
	s_cmp_gt_u32 s36, 5
	v_exp_f32_e32 v20, v20
	v_exp_f32_e32 v21, v21
	v_exp_f32_e32 v25, v22
	s_cselect_b64 s[0:1], -1, 0
	s_addk_i32 s31, 0xb0
	s_cmp_lt_u32 s36, 6
	s_cselect_b32 s31, s31, 0x80
	s_add_i32 s31, s31, s5
	v_pk_add_f32 v[22:23], v[20:21], v[24:25]
	v_cvt_pk_bf16_f32 v20, v20, v24
	v_cvt_pk_bf16_f32 v21, v21, v25
	s_nop 0
	s_nop 1
	v_mfma_f32_16x16x16_bf16 v[48:51], v[16:17], v[20:21], v[48:51]
	v_mfma_f32_16x16x16_bf16 v[68:71], v[18:19], v[20:21], v[68:71]
	v_mfma_f32_16x16x16_bf16 v[12:15], v[28:29], v[20:21], v[12:15]
	v_mfma_f32_16x16x16_bf16 v[8:11], v[30:31], v[20:21], v[8:11]
	s_nop 7
	v_or_b32_e32 v16, s31, v149
	v_lshl_add_u32 v16, v16, 4, s10
	v_add_u32_e32 v17, s31, v194
	v_med3_i32 v16, v16, 0, v244
	v_lshl_add_u32 v17, v17, 4, s10
	v_med3_i32 v18, v17, 0, v244
	v_mul_u32_u24_e32 v176, 0x2800, v16
	v_lshl_add_u64 v[16:17], v[72:73], 0, v[176:177]
	v_mul_u32_u24_e32 v176, 0x2800, v18
	v_add_f32_e32 v22, v22, v23
	v_lshl_add_u64 v[28:29], v[74:75], 0, v[176:177]
	v_add_f32_e32 v82, v81, v22
	global_load_dwordx4 v[20:23], v[16:17], off offset:2560
	global_load_dwordx4 v[24:27], v[16:17], off offset:2624
	s_nop 0
	global_load_dwordx4 v[16:19], v[28:29], off offset:16
	s_nop 0
	global_load_dwordx4 v[28:31], v[28:29], off
	ds_write_b128 v211, v[36:39]
	ds_write_b128 v211, v[32:35] offset:16
	ds_read_b64_tr_b16 v[32:33], v212
	ds_read_b64_tr_b16 v[34:35], v212 offset:32
	ds_read_b64_tr_b16 v[36:37], v212 offset:64
	ds_read_b64_tr_b16 v[38:39], v212 offset:96
	v_add_u32_e32 v81, 16, v79
	s_nop 1
	v_mfma_f32_16x16x32_bf16 v[84:87], v[40:43], v[0:3], 0
	v_mfma_f32_16x16x32_bf16 v[84:87], v[44:47], v[4:7], v[84:87]
	s_nop 7
	v_add_u32_e32 v40, 0x90, v77
	v_cmp_gt_u32_e32 vcc, s16, v40
	v_cmp_lt_i32_e64 s[44:45], -1, v81
	v_add_u32_e32 v41, 16, v77
	s_and_b64 vcc, s[44:45], vcc
	v_cndmask_b32_e32 v40, v245, v84, vcc
	v_cmp_lt_u32_e32 vcc, s17, v41
	v_cmp_lt_i32_e64 s[44:45], -2, v81
	s_and_b64 vcc, s[44:45], vcc
	v_add_u32_e32 v42, 0x92, v77
	v_cndmask_b32_e32 v41, v245, v85, vcc
	v_cmp_gt_u32_e32 vcc, s16, v42
	v_cmp_lt_i32_e64 s[44:45], -3, v81
	s_and_b64 vcc, s[44:45], vcc
	v_add_u32_e32 v43, 0x93, v77
	v_cndmask_b32_e32 v42, v245, v86, vcc
	v_cmp_gt_u32_e32 vcc, s16, v43
	v_cmp_lt_i32_e64 s[44:45], -4, v81
	s_and_b64 vcc, s[44:45], vcc
	v_cndmask_b32_e32 v43, v245, v87, vcc
	v_max_f32_e32 v44, v43, v43
	v_max_f32_e32 v45, v42, v42
	v_max_f32_e32 v44, v45, v44
	v_max3_f32 v44, v40, v41, v44
	ds_swizzle_b32 v45, v44 offset:swizzle(SWAP,16)
	s_waitcnt lgkmcnt(0)
	v_max_f32_e32 v45, v45, v45
	v_max_f32_e32 v44, v44, v45
	v_mov_b32_e32 v45, v44
	s_nop 1
	v_permlane32_swap_b32_e32 v44, v45
	v_max_f32_e32 v45, v45, v45
	v_max_f32_e32 v44, v44, v44
	v_max_f32_e32 v44, v44, v45
	v_mul_f32_e32 v44, 0x3e38aa3b, v44
	v_cmp_gt_f32_e32 vcc, v44, v80
	s_cbranch_vccz .LBB0_463
	s_nop 0
	v_cndmask_b32_e32 v45, v76, v44, vcc
	v_sub_f32_e32 v44, v76, v45
	v_exp_f32_e32 v44, v44
	v_xor_b32_e32 v81, 0x80000000, v45
	v_add_f32_e32 v80, 0x41000000, v45
	v_mov_b32_e32 v76, v45
	v_mul_f32_e32 v82, v82, v44
	v_pk_mul_f32 v[50:51], v[50:51], v[44:45] op_sel_hi:[1,0]
	v_pk_mul_f32 v[48:49], v[48:49], v[44:45] op_sel_hi:[1,0]
	v_pk_mul_f32 v[70:71], v[70:71], v[44:45] op_sel_hi:[1,0]
	v_pk_mul_f32 v[68:69], v[68:69], v[44:45] op_sel_hi:[1,0]
	v_pk_mul_f32 v[14:15], v[14:15], v[44:45] op_sel_hi:[1,0]
	v_pk_mul_f32 v[12:13], v[12:13], v[44:45] op_sel_hi:[1,0]
	v_pk_mul_f32 v[10:11], v[10:11], v[44:45] op_sel_hi:[1,0]
	v_pk_mul_f32 v[8:9], v[8:9], v[44:45] op_sel_hi:[1,0]
	s_branch .LBB0_464

.LBB0_464:
	v_fmamk_f32 v41, v41, 0x3e38aa3b, v81
	v_fmamk_f32 v40, v40, 0x3e38aa3b, v81
	v_exp_f32_e32 v44, v41
	v_fmamk_f32 v41, v42, 0x3e38aa3b, v81
	v_fmamk_f32 v42, v43, 0x3e38aa3b, v81
	v_exp_f32_e32 v40, v40
	v_exp_f32_e32 v41, v41
	v_exp_f32_e32 v45, v42
	s_min_u32 s31, s36, 4
	s_lshl_b32 s31, s31, 4
	s_add_i32 s31, s31, s37
	v_pk_add_f32 v[42:43], v[40:41], v[44:45]
	v_cvt_pk_bf16_f32 v40, v40, v44
	v_cvt_pk_bf16_f32 v41, v41, v45
	v_add_u32_e32 v79, 32, v79
	s_nop 1
	v_mfma_f32_16x16x16_bf16 v[48:51], v[32:33], v[40:41], v[48:51]
	v_mfma_f32_16x16x16_bf16 v[68:71], v[34:35], v[40:41], v[68:71]
	v_mfma_f32_16x16x16_bf16 v[12:15], v[36:37], v[40:41], v[12:15]
	v_mfma_f32_16x16x16_bf16 v[8:11], v[38:39], v[40:41], v[8:11]
	s_nop 7
	v_or_b32_e32 v32, s31, v149
	v_lshl_add_u32 v32, v32, 4, s10
	v_add_u32_e32 v33, s31, v194
	v_med3_i32 v32, v32, 0, v244
	v_lshl_add_u32 v33, v33, 4, s10
	v_med3_i32 v34, v33, 0, v244
	v_mul_u32_u24_e32 v176, 0x2800, v32
	v_lshl_add_u64 v[32:33], v[72:73], 0, v[176:177]
	v_mul_u32_u24_e32 v176, 0x2800, v34
	v_add_f32_e32 v42, v42, v43
	v_lshl_add_u64 v[36:37], v[74:75], 0, v[176:177]
	v_add_f32_e32 v82, v82, v42
	global_load_dwordx4 v[40:43], v[32:33], off offset:2560
	global_load_dwordx4 v[44:47], v[32:33], off offset:2624
	s_nop 0
	global_load_dwordx4 v[32:35], v[36:37], off offset:16
	s_nop 0
	global_load_dwordx4 v[36:39], v[36:37], off
	s_waitcnt vmcnt(8)
	ds_write_b128 v211, v[64:67]
	ds_write_b128 v211, v[60:63] offset:16
	ds_read_b64_tr_b16 v[60:61], v212
	ds_read_b64_tr_b16 v[62:63], v212 offset:32
	ds_read_b64_tr_b16 v[64:65], v212 offset:64
	ds_read_b64_tr_b16 v[66:67], v212 offset:96
	s_nop 1
	v_mfma_f32_16x16x32_bf16 v[84:87], v[52:55], v[0:3], 0
	v_mfma_f32_16x16x32_bf16 v[84:87], v[56:59], v[4:7], v[84:87]
	s_nop 7
	v_add_u32_e32 v52, 0xa0, v77
	v_cmp_gt_u32_e32 vcc, s16, v52
	v_cmp_lt_i32_e64 s[44:45], -1, v79
	v_add_u32_e32 v53, 32, v77
	s_and_b64 vcc, s[44:45], vcc
	v_cndmask_b32_e32 v52, v245, v84, vcc
	v_cmp_lt_u32_e32 vcc, s17, v53
	v_cmp_lt_i32_e64 s[44:45], -2, v79
	s_and_b64 vcc, s[44:45], vcc
	v_add_u32_e32 v54, 0xa2, v77
	v_cndmask_b32_e32 v53, v245, v85, vcc
	v_cmp_gt_u32_e32 vcc, s16, v54
	v_cmp_lt_i32_e64 s[44:45], -3, v79
	s_and_b64 vcc, s[44:45], vcc
	v_add_u32_e32 v55, 0xa3, v77
	v_cndmask_b32_e32 v54, v245, v86, vcc
	v_cmp_gt_u32_e32 vcc, s16, v55
	v_cmp_lt_i32_e64 s[44:45], -4, v79
	s_and_b64 vcc, s[44:45], vcc
	v_cndmask_b32_e32 v55, v245, v87, vcc
	v_max_f32_e32 v56, v55, v55
	v_max_f32_e32 v57, v54, v54
	v_max_f32_e32 v56, v57, v56
	v_max3_f32 v56, v52, v53, v56
	ds_swizzle_b32 v57, v56 offset:swizzle(SWAP,16)
	s_waitcnt lgkmcnt(0)
	v_max_f32_e32 v57, v57, v57
	v_max_f32_e32 v56, v56, v57
	v_mov_b32_e32 v57, v56
	s_nop 1
	v_permlane32_swap_b32_e32 v56, v57
	v_max_f32_e32 v57, v57, v57
	v_max_f32_e32 v56, v56, v56
	v_max_f32_e32 v56, v56, v57
	v_mul_f32_e32 v56, 0x3e38aa3b, v56
	v_cmp_gt_f32_e32 vcc, v56, v80
	s_cbranch_vccz .LBB0_458
	s_nop 0
	v_cndmask_b32_e32 v57, v76, v56, vcc
	v_sub_f32_e32 v56, v76, v57
	v_exp_f32_e32 v56, v56
	v_xor_b32_e32 v81, 0x80000000, v57
	v_mov_b32_e32 v76, v57
	v_mul_f32_e32 v82, v82, v56
	v_pk_mul_f32 v[50:51], v[50:51], v[56:57] op_sel_hi:[1,0]
	v_pk_mul_f32 v[48:49], v[48:49], v[56:57] op_sel_hi:[1,0]
	v_pk_mul_f32 v[70:71], v[70:71], v[56:57] op_sel_hi:[1,0]
	v_pk_mul_f32 v[68:69], v[68:69], v[56:57] op_sel_hi:[1,0]
	v_pk_mul_f32 v[14:15], v[14:15], v[56:57] op_sel_hi:[1,0]
	v_pk_mul_f32 v[12:13], v[12:13], v[56:57] op_sel_hi:[1,0]
	v_pk_mul_f32 v[10:11], v[10:11], v[56:57] op_sel_hi:[1,0]
	v_pk_mul_f32 v[8:9], v[8:9], v[56:57] op_sel_hi:[1,0]
	s_branch .LBB0_458
